# K-loops: s_setprio 0 after each exit barrier delayed until just before the next load part's first LDS-DMA load, so its ds_reads issue at priority 1
# baseline (speedup 1.0000x reference)
.LBB0_287:
	s_add_i32 m0, s53, 0xc000
	ds_read_b128 v[158:161], v165
	ds_read_b128 v[174:177], v165 offset:1024
	ds_read_b128 v[178:181], v165 offset:2048
	ds_read_b128 v[182:185], v165 offset:3072
	ds_read_b128 v[186:189], v165 offset:4096
	ds_read_b128 v[190:193], v165 offset:5120
	ds_read_b128 v[194:197], v165 offset:6144
	ds_read_b128 v[198:201], v165 offset:7168
	global_load_lds_dwordx4 v154, s[22:23]
	s_add_i32 m0, s53, 0xe000
	s_nop 0
	global_load_lds_dwordx4 v156, s[22:23]
	s_waitcnt vmcnt(10) lgkmcnt(8)
	s_setprio 1
	s_barrier
	s_waitcnt lgkmcnt(0)
	v_mfma_f32_16x16x32_bf16 v[144:147], v[68:71], v[158:161], v[144:147]
	v_mfma_f32_16x16x32_bf16 v[140:143], v[76:79], v[158:161], v[140:143]
	v_mfma_f32_16x16x32_bf16 v[128:131], v[68:71], v[178:181], v[128:131]
	v_mfma_f32_16x16x32_bf16 v[124:127], v[76:79], v[178:181], v[124:127]
	v_mfma_f32_16x16x32_bf16 v[112:115], v[68:71], v[186:189], v[112:115]
	v_mfma_f32_16x16x32_bf16 v[108:111], v[76:79], v[186:189], v[108:111]
	v_mfma_f32_16x16x32_bf16 v[96:99], v[68:71], v[194:197], v[96:99]
	v_mfma_f32_16x16x32_bf16 v[92:95], v[76:79], v[194:197], v[92:95]
	v_mfma_f32_16x16x32_bf16 v[144:147], v[72:75], v[174:177], v[144:147]
	v_mfma_f32_16x16x32_bf16 v[140:143], v[80:83], v[174:177], v[140:143]
	v_mfma_f32_16x16x32_bf16 v[128:131], v[72:75], v[182:185], v[128:131]
	v_mfma_f32_16x16x32_bf16 v[124:127], v[80:83], v[182:185], v[124:127]
	v_mfma_f32_16x16x32_bf16 v[112:115], v[72:75], v[190:193], v[112:115]
	v_mfma_f32_16x16x32_bf16 v[108:111], v[80:83], v[190:193], v[108:111]
	v_mfma_f32_16x16x32_bf16 v[96:99], v[72:75], v[198:201], v[96:99]
	v_mfma_f32_16x16x32_bf16 v[92:95], v[80:83], v[198:201], v[92:95]
	s_barrier
	s_add_i32 s73, 0, 0x14000
	s_add_i32 s0, s72, s52
	v_add_u32_e32 v166, s73, v163
	v_lshl_add_u64 v[218:219], s[24:25], 0, v[26:27]
	s_mov_b32 m0, s0
	ds_read_b128 v[202:205], v166
	ds_read_b128 v[206:209], v166 offset:1024
	ds_read_b128 v[210:213], v166 offset:2048
	ds_read_b128 v[214:217], v166 offset:3072
	s_setprio 0
	global_load_lds_dwordx4 v[218:219], off
	v_lshl_add_u64 v[220:221], s[24:25], 0, v[148:149]
	s_add_i32 m0, s0, 0x2000
	s_nop 0
	global_load_lds_dwordx4 v[220:221], off
	s_waitcnt vmcnt(10)
	s_setprio 1
	s_barrier
	s_waitcnt lgkmcnt(0)
	v_mfma_f32_16x16x32_bf16 v[136:139], v[202:205], v[158:161], v[136:139]
	v_mfma_f32_16x16x32_bf16 v[132:135], v[210:213], v[158:161], v[132:135]
	v_mfma_f32_16x16x32_bf16 v[120:123], v[202:205], v[178:181], v[120:123]
	v_mfma_f32_16x16x32_bf16 v[116:119], v[210:213], v[178:181], v[116:119]
	v_mfma_f32_16x16x32_bf16 v[104:107], v[202:205], v[186:189], v[104:107]
	v_mfma_f32_16x16x32_bf16 v[100:103], v[210:213], v[186:189], v[100:103]
	v_mfma_f32_16x16x32_bf16 v[88:91], v[202:205], v[194:197], v[88:91]
	v_mfma_f32_16x16x32_bf16 v[84:87], v[210:213], v[194:197], v[84:87]
	v_mfma_f32_16x16x32_bf16 v[136:139], v[206:209], v[174:177], v[136:139]
	v_mfma_f32_16x16x32_bf16 v[132:135], v[214:217], v[174:177], v[132:135]
	v_mfma_f32_16x16x32_bf16 v[120:123], v[206:209], v[182:185], v[120:123]
	v_mfma_f32_16x16x32_bf16 v[116:119], v[214:217], v[182:185], v[116:119]
	v_mfma_f32_16x16x32_bf16 v[104:107], v[206:209], v[190:193], v[104:107]
	v_mfma_f32_16x16x32_bf16 v[100:103], v[214:217], v[190:193], v[100:103]
	v_mfma_f32_16x16x32_bf16 v[88:91], v[206:209], v[198:201], v[88:91]
	v_mfma_f32_16x16x32_bf16 v[84:87], v[214:217], v[198:201], v[84:87]
	s_barrier
	s_mov_b32 m0, s53
	v_lshl_add_u64 v[222:223], s[26:27], 0, v[152:153]
	ds_read_b128 v[158:161], v165 offset:16384
	ds_read_b128 v[174:177], v165 offset:17408
	ds_read_b128 v[178:181], v165 offset:18432
	ds_read_b128 v[182:185], v165 offset:19456
	ds_read_b128 v[186:189], v165 offset:20480
	ds_read_b128 v[190:193], v165 offset:21504
	ds_read_b128 v[194:197], v165 offset:22528
	ds_read_b128 v[198:201], v165 offset:23552
	s_setprio 0
	global_load_lds_dwordx4 v[222:223], off
	v_lshl_add_u64 v[224:225], s[26:27], 0, v[150:151]
	s_mov_b32 m0, s54
	s_nop 0
	global_load_lds_dwordx4 v[224:225], off
	s_waitcnt vmcnt(10)
	s_setprio 1
	s_barrier
	s_waitcnt lgkmcnt(0)
	v_mfma_f32_16x16x32_bf16 v[64:67], v[68:71], v[158:161], v[64:67]
	v_mfma_f32_16x16x32_bf16 v[60:63], v[76:79], v[158:161], v[60:63]
	v_mfma_f32_16x16x32_bf16 v[48:51], v[68:71], v[178:181], v[48:51]
	v_mfma_f32_16x16x32_bf16 v[44:47], v[76:79], v[178:181], v[44:47]
	v_mfma_f32_16x16x32_bf16 v[32:35], v[68:71], v[186:189], v[32:35]
	v_mfma_f32_16x16x32_bf16 v[28:31], v[76:79], v[186:189], v[28:31]
	v_mfma_f32_16x16x32_bf16 v[14:17], v[68:71], v[194:197], v[14:17]
	v_mfma_f32_16x16x32_bf16 v[10:13], v[76:79], v[194:197], v[10:13]
	v_mfma_f32_16x16x32_bf16 v[64:67], v[72:75], v[174:177], v[64:67]
	v_mfma_f32_16x16x32_bf16 v[60:63], v[80:83], v[174:177], v[60:63]
	v_mfma_f32_16x16x32_bf16 v[48:51], v[72:75], v[182:185], v[48:51]
	v_mfma_f32_16x16x32_bf16 v[44:47], v[80:83], v[182:185], v[44:47]
	v_mfma_f32_16x16x32_bf16 v[32:35], v[72:75], v[190:193], v[32:35]
	v_mfma_f32_16x16x32_bf16 v[28:31], v[80:83], v[190:193], v[28:31]
	v_mfma_f32_16x16x32_bf16 v[14:17], v[72:75], v[198:201], v[14:17]
	v_mfma_f32_16x16x32_bf16 v[10:13], v[80:83], v[198:201], v[10:13]
	s_barrier
	s_add_u32 s0, s24, 0x40000
	s_addc_u32 s1, s25, 0
	s_add_i32 s72, s73, s52
	s_setprio 0
	s_mov_b32 m0, s72
	s_nop 0
	global_load_lds_dwordx4 v26, s[0:1]
	s_add_i32 m0, s72, 0x2000
	s_nop 0
	global_load_lds_dwordx4 v148, s[0:1]
	v_add_u32_e32 v80, 0x18000, v163
	ds_read_b128 v[68:71], v80
	ds_read_b128 v[72:75], v80 offset:1024
	ds_read_b128 v[76:79], v80 offset:2048
	ds_read_b128 v[80:83], v80 offset:3072
	s_waitcnt vmcnt(10)
	s_setprio 1
	s_barrier
	v_mfma_f32_16x16x32_bf16 v[56:59], v[202:205], v[158:161], v[56:59]
	v_mfma_f32_16x16x32_bf16 v[52:55], v[210:213], v[158:161], v[52:55]
	v_mfma_f32_16x16x32_bf16 v[40:43], v[202:205], v[178:181], v[40:43]
	v_mfma_f32_16x16x32_bf16 v[36:39], v[210:213], v[178:181], v[36:39]
	v_mfma_f32_16x16x32_bf16 v[22:25], v[202:205], v[186:189], v[22:25]
	v_mfma_f32_16x16x32_bf16 v[18:21], v[210:213], v[186:189], v[18:21]
	v_mfma_f32_16x16x32_bf16 v[6:9], v[202:205], v[194:197], v[6:9]
	v_mfma_f32_16x16x32_bf16 v[2:5], v[210:213], v[194:197], v[2:5]
	v_mfma_f32_16x16x32_bf16 v[56:59], v[206:209], v[174:177], v[56:59]
	v_mfma_f32_16x16x32_bf16 v[52:55], v[214:217], v[174:177], v[52:55]
	v_mfma_f32_16x16x32_bf16 v[40:43], v[206:209], v[182:185], v[40:43]
	v_mfma_f32_16x16x32_bf16 v[36:39], v[214:217], v[182:185], v[36:39]
	v_mfma_f32_16x16x32_bf16 v[22:25], v[206:209], v[190:193], v[22:25]
	v_mfma_f32_16x16x32_bf16 v[18:21], v[214:217], v[190:193], v[18:21]
	v_mfma_f32_16x16x32_bf16 v[6:9], v[206:209], v[198:201], v[6:9]
	v_mfma_f32_16x16x32_bf16 v[2:5], v[214:217], v[198:201], v[2:5]
	s_barrier
	s_add_i32 s72, 0, 0x18000
	s_add_u32 s0, s26, 0x40000
	s_addc_u32 s1, s27, 0
	s_mov_b32 m0, s55
	ds_read_b128 v[158:161], v165 offset:32768
	ds_read_b128 v[174:177], v165 offset:33792
	ds_read_b128 v[178:181], v165 offset:34816
	ds_read_b128 v[182:185], v165 offset:35840
	ds_read_b128 v[186:189], v165 offset:36864
	ds_read_b128 v[190:193], v165 offset:37888
	ds_read_b128 v[194:197], v165 offset:38912
	ds_read_b128 v[198:201], v165 offset:39936
	s_setprio 0
	global_load_lds_dwordx4 v152, s[0:1]
	s_mov_b32 m0, s56
	s_nop 0
	global_load_lds_dwordx4 v150, s[0:1]
	s_waitcnt vmcnt(10) lgkmcnt(8)
	s_setprio 1
	s_barrier
	s_waitcnt lgkmcnt(0)
	v_mfma_f32_16x16x32_bf16 v[144:147], v[68:71], v[158:161], v[144:147]
	v_mfma_f32_16x16x32_bf16 v[140:143], v[76:79], v[158:161], v[140:143]
	v_mfma_f32_16x16x32_bf16 v[128:131], v[68:71], v[178:181], v[128:131]
	v_mfma_f32_16x16x32_bf16 v[124:127], v[76:79], v[178:181], v[124:127]
	v_mfma_f32_16x16x32_bf16 v[112:115], v[68:71], v[186:189], v[112:115]
	v_mfma_f32_16x16x32_bf16 v[108:111], v[76:79], v[186:189], v[108:111]
	v_mfma_f32_16x16x32_bf16 v[96:99], v[68:71], v[194:197], v[96:99]
	v_mfma_f32_16x16x32_bf16 v[92:95], v[76:79], v[194:197], v[92:95]
	v_mfma_f32_16x16x32_bf16 v[144:147], v[72:75], v[174:177], v[144:147]
	v_mfma_f32_16x16x32_bf16 v[140:143], v[80:83], v[174:177], v[140:143]
	v_mfma_f32_16x16x32_bf16 v[128:131], v[72:75], v[182:185], v[128:131]
	v_mfma_f32_16x16x32_bf16 v[124:127], v[80:83], v[182:185], v[124:127]
	v_mfma_f32_16x16x32_bf16 v[112:115], v[72:75], v[190:193], v[112:115]
	v_mfma_f32_16x16x32_bf16 v[108:111], v[80:83], v[190:193], v[108:111]
	v_mfma_f32_16x16x32_bf16 v[96:99], v[72:75], v[198:201], v[96:99]
	v_mfma_f32_16x16x32_bf16 v[92:95], v[80:83], v[198:201], v[92:95]
	s_barrier
	s_add_i32 s26, 0, 0x1c000
	s_add_i32 s0, s72, s52
	v_add_u32_e32 v166, s26, v163
	v_lshl_add_u64 v[218:219], v[218:219], 0, s[12:13]
	s_mov_b32 m0, s0
	ds_read_b128 v[202:205], v166
	ds_read_b128 v[206:209], v166 offset:1024
	ds_read_b128 v[210:213], v166 offset:2048
	ds_read_b128 v[214:217], v166 offset:3072
	s_setprio 0
	global_load_lds_dwordx4 v[218:219], off
	v_lshl_add_u64 v[218:219], v[220:221], 0, s[12:13]
	s_add_i32 m0, s0, 0x2000
	s_nop 0
	global_load_lds_dwordx4 v[218:219], off
	s_waitcnt vmcnt(10)
	s_setprio 1
	s_barrier
	s_waitcnt lgkmcnt(0)
	v_mfma_f32_16x16x32_bf16 v[136:139], v[202:205], v[158:161], v[136:139]
	v_mfma_f32_16x16x32_bf16 v[132:135], v[210:213], v[158:161], v[132:135]
	v_mfma_f32_16x16x32_bf16 v[120:123], v[202:205], v[178:181], v[120:123]
	v_mfma_f32_16x16x32_bf16 v[116:119], v[210:213], v[178:181], v[116:119]
	v_mfma_f32_16x16x32_bf16 v[104:107], v[202:205], v[186:189], v[104:107]
	v_mfma_f32_16x16x32_bf16 v[100:103], v[210:213], v[186:189], v[100:103]
	v_mfma_f32_16x16x32_bf16 v[88:91], v[202:205], v[194:197], v[88:91]
	v_mfma_f32_16x16x32_bf16 v[84:87], v[210:213], v[194:197], v[84:87]
	v_mfma_f32_16x16x32_bf16 v[136:139], v[206:209], v[174:177], v[136:139]
	v_mfma_f32_16x16x32_bf16 v[132:135], v[214:217], v[174:177], v[132:135]
	v_mfma_f32_16x16x32_bf16 v[120:123], v[206:209], v[182:185], v[120:123]
	v_mfma_f32_16x16x32_bf16 v[116:119], v[214:217], v[182:185], v[116:119]
	v_mfma_f32_16x16x32_bf16 v[104:107], v[206:209], v[190:193], v[104:107]
	v_mfma_f32_16x16x32_bf16 v[100:103], v[214:217], v[190:193], v[100:103]
	v_mfma_f32_16x16x32_bf16 v[88:91], v[206:209], v[198:201], v[88:91]
	v_mfma_f32_16x16x32_bf16 v[84:87], v[214:217], v[198:201], v[84:87]
	s_barrier
	s_mov_b32 m0, s30
	v_lshl_add_u64 v[218:219], v[222:223], 0, s[12:13]
	ds_read_b128 v[158:161], v165 offset:49152
	ds_read_b128 v[174:177], v165 offset:50176
	ds_read_b128 v[178:181], v165 offset:51200
	ds_read_b128 v[182:185], v165 offset:52224
	ds_read_b128 v[186:189], v165 offset:53248
	ds_read_b128 v[190:193], v165 offset:54272
	ds_read_b128 v[194:197], v165 offset:55296
	ds_read_b128 v[198:201], v165 offset:56320
	s_setprio 0
	global_load_lds_dwordx4 v[218:219], off
	v_lshl_add_u64 v[218:219], v[224:225], 0, s[12:13]
	s_mov_b32 m0, s31
	s_nop 0
	global_load_lds_dwordx4 v[218:219], off
	s_waitcnt vmcnt(10)
	s_setprio 1
	s_barrier
	s_waitcnt lgkmcnt(0)
	v_mfma_f32_16x16x32_bf16 v[64:67], v[68:71], v[158:161], v[64:67]
	v_mfma_f32_16x16x32_bf16 v[60:63], v[76:79], v[158:161], v[60:63]
	v_mfma_f32_16x16x32_bf16 v[48:51], v[68:71], v[178:181], v[48:51]
	v_mfma_f32_16x16x32_bf16 v[44:47], v[76:79], v[178:181], v[44:47]
	v_mfma_f32_16x16x32_bf16 v[32:35], v[68:71], v[186:189], v[32:35]
	v_mfma_f32_16x16x32_bf16 v[28:31], v[76:79], v[186:189], v[28:31]
	v_mfma_f32_16x16x32_bf16 v[14:17], v[68:71], v[194:197], v[14:17]
	v_mfma_f32_16x16x32_bf16 v[10:13], v[76:79], v[194:197], v[10:13]
	v_mfma_f32_16x16x32_bf16 v[64:67], v[72:75], v[174:177], v[64:67]
	v_mfma_f32_16x16x32_bf16 v[60:63], v[80:83], v[174:177], v[60:63]
	v_mfma_f32_16x16x32_bf16 v[48:51], v[72:75], v[182:185], v[48:51]
	v_mfma_f32_16x16x32_bf16 v[44:47], v[80:83], v[182:185], v[44:47]
	v_mfma_f32_16x16x32_bf16 v[32:35], v[72:75], v[190:193], v[32:35]
	v_mfma_f32_16x16x32_bf16 v[28:31], v[80:83], v[190:193], v[28:31]
	v_mfma_f32_16x16x32_bf16 v[14:17], v[72:75], v[198:201], v[14:17]
	v_mfma_f32_16x16x32_bf16 v[10:13], v[80:83], v[198:201], v[10:13]
	s_barrier
	s_add_u32 s0, s24, 0x40080
	s_addc_u32 s1, s25, 0
	s_add_i32 s24, s26, s52
	s_setprio 0
	s_mov_b32 m0, s24
	s_nop 0
	global_load_lds_dwordx4 v26, s[0:1]
	s_add_i32 m0, s24, 0x2000
	s_nop 0
	global_load_lds_dwordx4 v148, s[0:1]
	v_add_u32_e32 v80, 0x10000, v163
	ds_read_b128 v[68:71], v80
	ds_read_b128 v[72:75], v80 offset:1024
	ds_read_b128 v[76:79], v80 offset:2048
	ds_read_b128 v[80:83], v80 offset:3072
	s_add_i32 s69, s69, 2
	s_add_u32 s22, s22, 0x100
	s_addc_u32 s23, s23, 0
	s_add_u32 s59, s59, 0x100
	s_addc_u32 s68, s68, 0
	s_cmp_gt_u32 s69, 13
	s_cbranch_scc1 .Lth__287
	s_add_u32 s0, s22, 0xfffc0080
	s_addc_u32 s1, s23, -1
	s_add_i32 s72, 0, 0x10000
	s_cmp_eq_u32 s69, 12
	s_cselect_b32 s27, s18, s1
	s_cselect_b32 s26, s19, s0
	s_cselect_b32 s25, s45, s68
	s_cselect_b32 s24, s47, s59
	s_cmp_gt_u32 s69, 13

.LBB0_361:
	s_add_i32 m0, s20, 0xc000
	ds_read_b128 v[172:175], v224
	ds_read_b128 v[176:179], v224 offset:1024
	ds_read_b128 v[180:183], v224 offset:2048
	ds_read_b128 v[184:187], v224 offset:3072
	ds_read_b128 v[188:191], v224 offset:4096
	ds_read_b128 v[192:195], v224 offset:5120
	ds_read_b128 v[196:199], v224 offset:6144
	ds_read_b128 v[200:203], v224 offset:7168
	global_load_lds_dwordx4 v152, s[26:27]
	v_lshl_add_u64 v[164:165], s[26:27], 0, v[154:155]
	s_add_i32 m0, s20, 0xe000
	s_nop 0
	global_load_lds_dwordx4 v[164:165], off
	s_waitcnt vmcnt(10) lgkmcnt(8)
	s_setprio 1
	s_barrier
	s_waitcnt lgkmcnt(0)
	v_mfma_f32_16x16x32_bf16 v[128:131], v[132:135], v[172:175], v[128:131]
	v_mfma_f32_16x16x32_bf16 v[124:127], v[156:159], v[172:175], v[124:127]
	v_mfma_f32_16x16x32_bf16 v[120:123], v[132:135], v[180:183], v[120:123]
	v_mfma_f32_16x16x32_bf16 v[116:119], v[156:159], v[180:183], v[116:119]
	v_mfma_f32_16x16x32_bf16 v[112:115], v[132:135], v[188:191], v[112:115]
	v_mfma_f32_16x16x32_bf16 v[108:111], v[156:159], v[188:191], v[108:111]
	v_mfma_f32_16x16x32_bf16 v[104:107], v[132:135], v[196:199], v[104:107]
	v_mfma_f32_16x16x32_bf16 v[100:103], v[156:159], v[196:199], v[100:103]
	v_mfma_f32_16x16x32_bf16 v[128:131], v[136:139], v[176:179], v[128:131]
	v_mfma_f32_16x16x32_bf16 v[124:127], v[160:163], v[176:179], v[124:127]
	v_mfma_f32_16x16x32_bf16 v[120:123], v[136:139], v[184:187], v[120:123]
	v_mfma_f32_16x16x32_bf16 v[116:119], v[160:163], v[184:187], v[116:119]
	v_mfma_f32_16x16x32_bf16 v[112:115], v[136:139], v[192:195], v[112:115]
	v_mfma_f32_16x16x32_bf16 v[108:111], v[160:163], v[192:195], v[108:111]
	v_mfma_f32_16x16x32_bf16 v[104:107], v[136:139], v[200:203], v[104:107]
	v_mfma_f32_16x16x32_bf16 v[100:103], v[160:163], v[200:203], v[100:103]
	s_barrier
	s_add_i32 s26, 0, 0x14000
	v_add_u32_e32 v164, s26, v222
	s_add_i32 s0, s0, s17
	ds_read_b128 v[204:207], v164
	ds_read_b128 v[208:211], v164 offset:1024
	ds_read_b128 v[212:215], v164 offset:2048
	ds_read_b128 v[216:219], v164 offset:3072
	v_lshl_add_u64 v[164:165], s[30:31], 0, v[26:27]
	s_mov_b32 m0, s0
	v_lshl_add_u64 v[166:167], s[30:31], 0, v[140:141]
	s_setprio 0
	global_load_lds_dwordx4 v[164:165], off
	s_add_i32 m0, s0, 0x2000
	s_nop 0
	global_load_lds_dwordx4 v[166:167], off
	s_waitcnt vmcnt(10)
	s_setprio 1
	s_barrier
	s_waitcnt lgkmcnt(0)
	v_mfma_f32_16x16x32_bf16 v[64:67], v[204:207], v[172:175], v[64:67]
	v_mfma_f32_16x16x32_bf16 v[60:63], v[212:215], v[172:175], v[60:63]
	v_mfma_f32_16x16x32_bf16 v[56:59], v[204:207], v[180:183], v[56:59]
	v_mfma_f32_16x16x32_bf16 v[52:55], v[212:215], v[180:183], v[52:55]
	v_mfma_f32_16x16x32_bf16 v[48:51], v[204:207], v[188:191], v[48:51]
	v_mfma_f32_16x16x32_bf16 v[44:47], v[212:215], v[188:191], v[44:47]
	v_mfma_f32_16x16x32_bf16 v[40:43], v[204:207], v[196:199], v[40:43]
	v_mfma_f32_16x16x32_bf16 v[36:39], v[212:215], v[196:199], v[36:39]
	v_mfma_f32_16x16x32_bf16 v[64:67], v[208:211], v[176:179], v[64:67]
	v_mfma_f32_16x16x32_bf16 v[60:63], v[216:219], v[176:179], v[60:63]
	v_mfma_f32_16x16x32_bf16 v[56:59], v[208:211], v[184:187], v[56:59]
	v_mfma_f32_16x16x32_bf16 v[52:55], v[216:219], v[184:187], v[52:55]
	v_mfma_f32_16x16x32_bf16 v[48:51], v[208:211], v[192:195], v[48:51]
	v_mfma_f32_16x16x32_bf16 v[44:47], v[216:219], v[192:195], v[44:47]
	v_mfma_f32_16x16x32_bf16 v[40:43], v[208:211], v[200:203], v[40:43]
	v_mfma_f32_16x16x32_bf16 v[36:39], v[216:219], v[200:203], v[36:39]
	s_barrier
	s_mov_b32 m0, s20
	v_lshl_add_u64 v[168:169], s[34:35], 0, v[144:145]
	ds_read_b128 v[172:175], v224 offset:16384
	ds_read_b128 v[176:179], v224 offset:17408
	ds_read_b128 v[180:183], v224 offset:18432
	ds_read_b128 v[184:187], v224 offset:19456
	ds_read_b128 v[188:191], v224 offset:20480
	ds_read_b128 v[192:195], v224 offset:21504
	ds_read_b128 v[196:199], v224 offset:22528
	ds_read_b128 v[200:203], v224 offset:23552
	s_setprio 0
	global_load_lds_dwordx4 v[168:169], off
	v_lshl_add_u64 v[220:221], s[34:35], 0, v[142:143]
	s_mov_b32 m0, s21
	s_nop 0
	global_load_lds_dwordx4 v[220:221], off
	s_waitcnt vmcnt(10)
	s_setprio 1
	s_barrier
	s_waitcnt lgkmcnt(0)
	v_mfma_f32_16x16x32_bf16 v[96:99], v[132:135], v[172:175], v[96:99]
	v_mfma_f32_16x16x32_bf16 v[92:95], v[156:159], v[172:175], v[92:95]
	v_mfma_f32_16x16x32_bf16 v[88:91], v[132:135], v[180:183], v[88:91]
	v_mfma_f32_16x16x32_bf16 v[84:87], v[156:159], v[180:183], v[84:87]
	v_mfma_f32_16x16x32_bf16 v[80:83], v[132:135], v[188:191], v[80:83]
	v_mfma_f32_16x16x32_bf16 v[76:79], v[156:159], v[188:191], v[76:79]
	v_mfma_f32_16x16x32_bf16 v[72:75], v[132:135], v[196:199], v[72:75]
	v_mfma_f32_16x16x32_bf16 v[68:71], v[156:159], v[196:199], v[68:71]
	v_mfma_f32_16x16x32_bf16 v[96:99], v[136:139], v[176:179], v[96:99]
	v_mfma_f32_16x16x32_bf16 v[92:95], v[160:163], v[176:179], v[92:95]
	v_mfma_f32_16x16x32_bf16 v[88:91], v[136:139], v[184:187], v[88:91]
	v_mfma_f32_16x16x32_bf16 v[84:87], v[160:163], v[184:187], v[84:87]
	v_mfma_f32_16x16x32_bf16 v[80:83], v[136:139], v[192:195], v[80:83]
	v_mfma_f32_16x16x32_bf16 v[76:79], v[160:163], v[192:195], v[76:79]
	v_mfma_f32_16x16x32_bf16 v[72:75], v[136:139], v[200:203], v[72:75]
	v_mfma_f32_16x16x32_bf16 v[68:71], v[160:163], v[200:203], v[68:71]
	s_barrier
	s_add_u32 s0, s30, 0xb0000
	s_addc_u32 s1, s31, 0
	s_add_i32 s26, s26, s17
	s_setprio 0
	s_mov_b32 m0, s26
	s_nop 0
	global_load_lds_dwordx4 v26, s[0:1]
	s_add_i32 m0, s26, 0x2000
	s_nop 0
	global_load_lds_dwordx4 v140, s[0:1]
	v_add_u32_e32 v160, 0x18000, v222
	ds_read_b128 v[132:135], v160
	ds_read_b128 v[136:139], v160 offset:1024
	ds_read_b128 v[156:159], v160 offset:2048
	ds_read_b128 v[160:163], v160 offset:3072
	s_waitcnt vmcnt(10)
	s_setprio 1
	s_barrier
	v_mfma_f32_16x16x32_bf16 v[32:35], v[204:207], v[172:175], v[32:35]
	v_mfma_f32_16x16x32_bf16 v[28:31], v[212:215], v[172:175], v[28:31]
	v_mfma_f32_16x16x32_bf16 v[22:25], v[204:207], v[180:183], v[22:25]
	v_mfma_f32_16x16x32_bf16 v[18:21], v[212:215], v[180:183], v[18:21]
	v_mfma_f32_16x16x32_bf16 v[14:17], v[204:207], v[188:191], v[14:17]
	v_mfma_f32_16x16x32_bf16 v[10:13], v[212:215], v[188:191], v[10:13]
	v_mfma_f32_16x16x32_bf16 v[6:9], v[204:207], v[196:199], v[6:9]
	v_mfma_f32_16x16x32_bf16 v[2:5], v[212:215], v[196:199], v[2:5]
	v_mfma_f32_16x16x32_bf16 v[32:35], v[208:211], v[176:179], v[32:35]
	v_mfma_f32_16x16x32_bf16 v[28:31], v[216:219], v[176:179], v[28:31]
	v_mfma_f32_16x16x32_bf16 v[22:25], v[208:211], v[184:187], v[22:25]
	v_mfma_f32_16x16x32_bf16 v[18:21], v[216:219], v[184:187], v[18:21]
	v_mfma_f32_16x16x32_bf16 v[14:17], v[208:211], v[192:195], v[14:17]
	v_mfma_f32_16x16x32_bf16 v[10:13], v[216:219], v[192:195], v[10:13]
	v_mfma_f32_16x16x32_bf16 v[6:9], v[208:211], v[200:203], v[6:9]
	v_mfma_f32_16x16x32_bf16 v[2:5], v[216:219], v[200:203], v[2:5]
	s_barrier
	s_add_i32 s26, 0, 0x18000
	s_add_u32 s0, s34, 0xb0000
	s_addc_u32 s1, s35, 0
	s_mov_b32 m0, s36
	ds_read_b128 v[172:175], v224 offset:32768
	ds_read_b128 v[176:179], v224 offset:33792
	ds_read_b128 v[180:183], v224 offset:34816
	ds_read_b128 v[184:187], v224 offset:35840
	ds_read_b128 v[188:191], v224 offset:36864
	ds_read_b128 v[192:195], v224 offset:37888
	ds_read_b128 v[196:199], v224 offset:38912
	ds_read_b128 v[200:203], v224 offset:39936
	s_setprio 0
	global_load_lds_dwordx4 v144, s[0:1]
	s_mov_b32 m0, s37
	s_nop 0
	global_load_lds_dwordx4 v142, s[0:1]
	s_waitcnt vmcnt(10) lgkmcnt(8)
	s_setprio 1
	s_barrier
	s_waitcnt lgkmcnt(0)
	v_mfma_f32_16x16x32_bf16 v[128:131], v[132:135], v[172:175], v[128:131]
	v_mfma_f32_16x16x32_bf16 v[124:127], v[156:159], v[172:175], v[124:127]
	v_mfma_f32_16x16x32_bf16 v[120:123], v[132:135], v[180:183], v[120:123]
	v_mfma_f32_16x16x32_bf16 v[116:119], v[156:159], v[180:183], v[116:119]
	v_mfma_f32_16x16x32_bf16 v[112:115], v[132:135], v[188:191], v[112:115]
	v_mfma_f32_16x16x32_bf16 v[108:111], v[156:159], v[188:191], v[108:111]
	v_mfma_f32_16x16x32_bf16 v[104:107], v[132:135], v[196:199], v[104:107]
	v_mfma_f32_16x16x32_bf16 v[100:103], v[156:159], v[196:199], v[100:103]
	v_mfma_f32_16x16x32_bf16 v[128:131], v[136:139], v[176:179], v[128:131]
	v_mfma_f32_16x16x32_bf16 v[124:127], v[160:163], v[176:179], v[124:127]
	v_mfma_f32_16x16x32_bf16 v[120:123], v[136:139], v[184:187], v[120:123]
	v_mfma_f32_16x16x32_bf16 v[116:119], v[160:163], v[184:187], v[116:119]
	v_mfma_f32_16x16x32_bf16 v[112:115], v[136:139], v[192:195], v[112:115]
	v_mfma_f32_16x16x32_bf16 v[108:111], v[160:163], v[192:195], v[108:111]
	v_mfma_f32_16x16x32_bf16 v[104:107], v[136:139], v[200:203], v[104:107]
	v_mfma_f32_16x16x32_bf16 v[100:103], v[160:163], v[200:203], v[100:103]
	s_barrier
	s_add_i32 s27, 0, 0x1c000
	s_add_i32 s0, s26, s17
	v_add_u32_e32 v216, s27, v222
	v_lshl_add_u64 v[164:165], v[164:165], 0, s[12:13]
	s_mov_b32 m0, s0
	ds_read_b128 v[204:207], v216
	ds_read_b128 v[208:211], v216 offset:1024
	ds_read_b128 v[212:215], v216 offset:2048
	ds_read_b128 v[216:219], v216 offset:3072
	s_setprio 0
	global_load_lds_dwordx4 v[164:165], off
	v_lshl_add_u64 v[164:165], v[166:167], 0, s[12:13]
	s_add_i32 m0, s0, 0x2000
	s_nop 0
	global_load_lds_dwordx4 v[164:165], off
	s_waitcnt vmcnt(10)
	s_setprio 1
	s_barrier
	s_waitcnt lgkmcnt(0)
	v_mfma_f32_16x16x32_bf16 v[64:67], v[204:207], v[172:175], v[64:67]
	v_mfma_f32_16x16x32_bf16 v[60:63], v[212:215], v[172:175], v[60:63]
	v_mfma_f32_16x16x32_bf16 v[56:59], v[204:207], v[180:183], v[56:59]
	v_mfma_f32_16x16x32_bf16 v[52:55], v[212:215], v[180:183], v[52:55]
	v_mfma_f32_16x16x32_bf16 v[48:51], v[204:207], v[188:191], v[48:51]
	v_mfma_f32_16x16x32_bf16 v[44:47], v[212:215], v[188:191], v[44:47]
	v_mfma_f32_16x16x32_bf16 v[40:43], v[204:207], v[196:199], v[40:43]
	v_mfma_f32_16x16x32_bf16 v[36:39], v[212:215], v[196:199], v[36:39]
	v_mfma_f32_16x16x32_bf16 v[64:67], v[208:211], v[176:179], v[64:67]
	v_mfma_f32_16x16x32_bf16 v[60:63], v[216:219], v[176:179], v[60:63]
	v_mfma_f32_16x16x32_bf16 v[56:59], v[208:211], v[184:187], v[56:59]
	v_mfma_f32_16x16x32_bf16 v[52:55], v[216:219], v[184:187], v[52:55]
	v_mfma_f32_16x16x32_bf16 v[48:51], v[208:211], v[192:195], v[48:51]
	v_mfma_f32_16x16x32_bf16 v[44:47], v[216:219], v[192:195], v[44:47]
	v_mfma_f32_16x16x32_bf16 v[40:43], v[208:211], v[200:203], v[40:43]
	v_mfma_f32_16x16x32_bf16 v[36:39], v[216:219], v[200:203], v[36:39]
	s_barrier
	s_mov_b32 m0, s59
	v_lshl_add_u64 v[164:165], v[168:169], 0, s[12:13]
	ds_read_b128 v[172:175], v224 offset:49152
	ds_read_b128 v[176:179], v224 offset:50176
	ds_read_b128 v[180:183], v224 offset:51200
	ds_read_b128 v[184:187], v224 offset:52224
	ds_read_b128 v[188:191], v224 offset:53248
	ds_read_b128 v[192:195], v224 offset:54272
	ds_read_b128 v[196:199], v224 offset:55296
	ds_read_b128 v[200:203], v224 offset:56320
	s_setprio 0
	global_load_lds_dwordx4 v[164:165], off
	v_lshl_add_u64 v[164:165], v[220:221], 0, s[12:13]
	s_mov_b32 m0, s68
	s_nop 0
	global_load_lds_dwordx4 v[164:165], off
	s_waitcnt vmcnt(10)
	s_setprio 1
	s_barrier
	s_waitcnt lgkmcnt(0)
	v_mfma_f32_16x16x32_bf16 v[96:99], v[132:135], v[172:175], v[96:99]
	v_mfma_f32_16x16x32_bf16 v[92:95], v[156:159], v[172:175], v[92:95]
	v_mfma_f32_16x16x32_bf16 v[88:91], v[132:135], v[180:183], v[88:91]
	v_mfma_f32_16x16x32_bf16 v[84:87], v[156:159], v[180:183], v[84:87]
	v_mfma_f32_16x16x32_bf16 v[80:83], v[132:135], v[188:191], v[80:83]
	v_mfma_f32_16x16x32_bf16 v[76:79], v[156:159], v[188:191], v[76:79]
	v_mfma_f32_16x16x32_bf16 v[72:75], v[132:135], v[196:199], v[72:75]
	v_mfma_f32_16x16x32_bf16 v[68:71], v[156:159], v[196:199], v[68:71]
	v_mfma_f32_16x16x32_bf16 v[96:99], v[136:139], v[176:179], v[96:99]
	v_mfma_f32_16x16x32_bf16 v[92:95], v[160:163], v[176:179], v[92:95]
	v_mfma_f32_16x16x32_bf16 v[88:91], v[136:139], v[184:187], v[88:91]
	v_mfma_f32_16x16x32_bf16 v[84:87], v[160:163], v[184:187], v[84:87]
	v_mfma_f32_16x16x32_bf16 v[80:83], v[136:139], v[192:195], v[80:83]
	v_mfma_f32_16x16x32_bf16 v[76:79], v[160:163], v[192:195], v[76:79]
	v_mfma_f32_16x16x32_bf16 v[72:75], v[136:139], v[200:203], v[72:75]
	v_mfma_f32_16x16x32_bf16 v[68:71], v[160:163], v[200:203], v[68:71]
	s_barrier
	s_add_u32 s0, s30, 0xb0080
	s_addc_u32 s1, s31, 0
	s_add_i32 s26, s27, s17
	s_setprio 0
	s_mov_b32 m0, s26
	s_nop 0
	global_load_lds_dwordx4 v26, s[0:1]
	s_add_i32 m0, s26, 0x2000
	s_nop 0
	global_load_lds_dwordx4 v140, s[0:1]
	v_add_u32_e32 v160, 0x10000, v222
	ds_read_b128 v[132:135], v160
	ds_read_b128 v[136:139], v160 offset:1024
	ds_read_b128 v[156:159], v160 offset:2048
	ds_read_b128 v[160:163], v160 offset:3072
	s_add_i32 s46, s46, 2
	s_add_u32 s18, s18, 0x100
	s_addc_u32 s19, s19, 0
	s_mov_b64 s[26:27], s[28:29]
	s_cmp_gt_u32 s46, 41
	s_cbranch_scc1 .Lth__361
	s_add_u32 s28, s26, 0x100
	s_addc_u32 s29, s27, 0
	s_add_i32 s0, 0, 0x10000
	s_cmp_eq_u32 s46, 40
	s_cselect_b32 s35, s45, s29
	s_cselect_b32 s34, s44, s28
	s_cselect_b32 s31, s23, s19
	s_cselect_b32 s30, s22, s18
	s_cmp_gt_u32 s46, 41

.LBB0_395:
	s_add_i32 m0, s69, 0xc000
	ds_read_b128 v[172:175], v235
	ds_read_b128 v[176:179], v235 offset:1024
	ds_read_b128 v[180:183], v235 offset:2048
	ds_read_b128 v[184:187], v235 offset:3072
	ds_read_b128 v[188:191], v235 offset:4096
	ds_read_b128 v[192:195], v235 offset:5120
	ds_read_b128 v[196:199], v235 offset:6144
	ds_read_b128 v[200:203], v235 offset:7168
	global_load_lds_dwordx4 v152, s[24:25]
	v_lshl_add_u64 v[164:165], s[24:25], 0, v[154:155]
	s_add_i32 m0, s69, 0xe000
	s_nop 0
	global_load_lds_dwordx4 v[164:165], off
	s_waitcnt vmcnt(10) lgkmcnt(8)
	s_setprio 1
	s_barrier
	s_waitcnt lgkmcnt(0)
	v_mfma_f32_16x16x32_bf16 v[136:139], v[100:103], v[172:175], v[136:139]
	v_mfma_f32_16x16x32_bf16 v[132:135], v[156:159], v[172:175], v[132:135]
	v_mfma_f32_16x16x32_bf16 v[128:131], v[100:103], v[180:183], v[128:131]
	v_mfma_f32_16x16x32_bf16 v[124:127], v[156:159], v[180:183], v[124:127]
	v_mfma_f32_16x16x32_bf16 v[120:123], v[100:103], v[188:191], v[120:123]
	v_mfma_f32_16x16x32_bf16 v[116:119], v[156:159], v[188:191], v[116:119]
	v_mfma_f32_16x16x32_bf16 v[112:115], v[100:103], v[196:199], v[112:115]
	v_mfma_f32_16x16x32_bf16 v[108:111], v[156:159], v[196:199], v[108:111]
	v_mfma_f32_16x16x32_bf16 v[136:139], v[104:107], v[176:179], v[136:139]
	v_mfma_f32_16x16x32_bf16 v[132:135], v[160:163], v[176:179], v[132:135]
	v_mfma_f32_16x16x32_bf16 v[128:131], v[104:107], v[184:187], v[128:131]
	v_mfma_f32_16x16x32_bf16 v[124:127], v[160:163], v[184:187], v[124:127]
	v_mfma_f32_16x16x32_bf16 v[120:123], v[104:107], v[192:195], v[120:123]
	v_mfma_f32_16x16x32_bf16 v[116:119], v[160:163], v[192:195], v[116:119]
	v_mfma_f32_16x16x32_bf16 v[112:115], v[104:107], v[200:203], v[112:115]
	v_mfma_f32_16x16x32_bf16 v[108:111], v[160:163], v[200:203], v[108:111]
	s_barrier
	s_add_i32 s24, 0, 0x14000
	v_add_u32_e32 v164, s24, v233
	s_add_i32 s0, s0, s68
	ds_read_b128 v[204:207], v164
	ds_read_b128 v[208:211], v164 offset:1024
	ds_read_b128 v[212:215], v164 offset:2048
	ds_read_b128 v[216:219], v164 offset:3072
	v_lshl_add_u64 v[164:165], s[28:29], 0, v[26:27]
	s_mov_b32 m0, s0
	v_lshl_add_u64 v[220:221], s[28:29], 0, v[140:141]
	s_setprio 0
	global_load_lds_dwordx4 v[164:165], off
	s_add_i32 m0, s0, 0x2000
	s_nop 0
	global_load_lds_dwordx4 v[220:221], off
	s_waitcnt vmcnt(10)
	s_setprio 1
	s_barrier
	s_waitcnt lgkmcnt(0)
	v_mfma_f32_16x16x32_bf16 v[64:67], v[204:207], v[172:175], v[64:67]
	v_mfma_f32_16x16x32_bf16 v[60:63], v[212:215], v[172:175], v[60:63]
	v_mfma_f32_16x16x32_bf16 v[56:59], v[204:207], v[180:183], v[56:59]
	v_mfma_f32_16x16x32_bf16 v[52:55], v[212:215], v[180:183], v[52:55]
	v_mfma_f32_16x16x32_bf16 v[48:51], v[204:207], v[188:191], v[48:51]
	v_mfma_f32_16x16x32_bf16 v[44:47], v[212:215], v[188:191], v[44:47]
	v_mfma_f32_16x16x32_bf16 v[40:43], v[204:207], v[196:199], v[40:43]
	v_mfma_f32_16x16x32_bf16 v[36:39], v[212:215], v[196:199], v[36:39]
	v_mfma_f32_16x16x32_bf16 v[64:67], v[208:211], v[176:179], v[64:67]
	v_mfma_f32_16x16x32_bf16 v[60:63], v[216:219], v[176:179], v[60:63]
	v_mfma_f32_16x16x32_bf16 v[56:59], v[208:211], v[184:187], v[56:59]
	v_mfma_f32_16x16x32_bf16 v[52:55], v[216:219], v[184:187], v[52:55]
	v_mfma_f32_16x16x32_bf16 v[48:51], v[208:211], v[192:195], v[48:51]
	v_mfma_f32_16x16x32_bf16 v[44:47], v[216:219], v[192:195], v[44:47]
	v_mfma_f32_16x16x32_bf16 v[40:43], v[208:211], v[200:203], v[40:43]
	v_mfma_f32_16x16x32_bf16 v[36:39], v[216:219], v[200:203], v[36:39]
	s_barrier
	s_mov_b32 m0, s69
	v_lshl_add_u64 v[222:223], s[30:31], 0, v[144:145]
	ds_read_b128 v[172:175], v235 offset:16384
	ds_read_b128 v[176:179], v235 offset:17408
	ds_read_b128 v[180:183], v235 offset:18432
	ds_read_b128 v[184:187], v235 offset:19456
	ds_read_b128 v[188:191], v235 offset:20480
	ds_read_b128 v[192:195], v235 offset:21504
	ds_read_b128 v[196:199], v235 offset:22528
	ds_read_b128 v[200:203], v235 offset:23552
	s_setprio 0
	global_load_lds_dwordx4 v[222:223], off
	v_lshl_add_u64 v[224:225], s[30:31], 0, v[142:143]
	s_mov_b32 m0, s72
	s_nop 0
	global_load_lds_dwordx4 v[224:225], off
	s_waitcnt vmcnt(10)
	s_setprio 1
	s_barrier
	s_waitcnt lgkmcnt(0)
	v_mfma_f32_16x16x32_bf16 v[96:99], v[100:103], v[172:175], v[96:99]
	v_mfma_f32_16x16x32_bf16 v[92:95], v[156:159], v[172:175], v[92:95]
	v_mfma_f32_16x16x32_bf16 v[88:91], v[100:103], v[180:183], v[88:91]
	v_mfma_f32_16x16x32_bf16 v[84:87], v[156:159], v[180:183], v[84:87]
	v_mfma_f32_16x16x32_bf16 v[80:83], v[100:103], v[188:191], v[80:83]
	v_mfma_f32_16x16x32_bf16 v[76:79], v[156:159], v[188:191], v[76:79]
	v_mfma_f32_16x16x32_bf16 v[72:75], v[100:103], v[196:199], v[72:75]
	v_mfma_f32_16x16x32_bf16 v[68:71], v[156:159], v[196:199], v[68:71]
	v_mfma_f32_16x16x32_bf16 v[96:99], v[104:107], v[176:179], v[96:99]
	v_mfma_f32_16x16x32_bf16 v[92:95], v[160:163], v[176:179], v[92:95]
	v_mfma_f32_16x16x32_bf16 v[88:91], v[104:107], v[184:187], v[88:91]
	v_mfma_f32_16x16x32_bf16 v[84:87], v[160:163], v[184:187], v[84:87]
	v_mfma_f32_16x16x32_bf16 v[80:83], v[104:107], v[192:195], v[80:83]
	v_mfma_f32_16x16x32_bf16 v[76:79], v[160:163], v[192:195], v[76:79]
	v_mfma_f32_16x16x32_bf16 v[72:75], v[104:107], v[200:203], v[72:75]
	v_mfma_f32_16x16x32_bf16 v[68:71], v[160:163], v[200:203], v[68:71]
	s_barrier
	s_add_u32 s0, s28, 0xb0000
	s_addc_u32 s1, s29, 0
	s_add_i32 s24, s24, s68
	s_setprio 0
	s_mov_b32 m0, s24
	s_nop 0
	global_load_lds_dwordx4 v26, s[0:1]
	s_add_i32 m0, s24, 0x2000
	s_nop 0
	global_load_lds_dwordx4 v140, s[0:1]
	v_add_u32_e32 v160, 0x18000, v233
	ds_read_b128 v[100:103], v160
	ds_read_b128 v[104:107], v160 offset:1024
	ds_read_b128 v[156:159], v160 offset:2048
	ds_read_b128 v[160:163], v160 offset:3072
	s_waitcnt vmcnt(10)
	s_setprio 1
	s_barrier
	v_mfma_f32_16x16x32_bf16 v[32:35], v[204:207], v[172:175], v[32:35]
	v_mfma_f32_16x16x32_bf16 v[28:31], v[212:215], v[172:175], v[28:31]
	v_mfma_f32_16x16x32_bf16 v[22:25], v[204:207], v[180:183], v[22:25]
	v_mfma_f32_16x16x32_bf16 v[18:21], v[212:215], v[180:183], v[18:21]
	v_mfma_f32_16x16x32_bf16 v[14:17], v[204:207], v[188:191], v[14:17]
	v_mfma_f32_16x16x32_bf16 v[10:13], v[212:215], v[188:191], v[10:13]
	v_mfma_f32_16x16x32_bf16 v[6:9], v[204:207], v[196:199], v[6:9]
	v_mfma_f32_16x16x32_bf16 v[2:5], v[212:215], v[196:199], v[2:5]
	v_mfma_f32_16x16x32_bf16 v[32:35], v[208:211], v[176:179], v[32:35]
	v_mfma_f32_16x16x32_bf16 v[28:31], v[216:219], v[176:179], v[28:31]
	v_mfma_f32_16x16x32_bf16 v[22:25], v[208:211], v[184:187], v[22:25]
	v_mfma_f32_16x16x32_bf16 v[18:21], v[216:219], v[184:187], v[18:21]
	v_mfma_f32_16x16x32_bf16 v[14:17], v[208:211], v[192:195], v[14:17]
	v_mfma_f32_16x16x32_bf16 v[10:13], v[216:219], v[192:195], v[10:13]
	v_mfma_f32_16x16x32_bf16 v[6:9], v[208:211], v[200:203], v[6:9]
	v_mfma_f32_16x16x32_bf16 v[2:5], v[216:219], v[200:203], v[2:5]
	s_barrier
	s_add_i32 s24, 0, 0x18000
	s_add_u32 s0, s30, 0xb0000
	s_addc_u32 s1, s31, 0
	s_mov_b32 m0, s73
	ds_read_b128 v[172:175], v235 offset:32768
	ds_read_b128 v[176:179], v235 offset:33792
	ds_read_b128 v[180:183], v235 offset:34816
	ds_read_b128 v[184:187], v235 offset:35840
	ds_read_b128 v[188:191], v235 offset:36864
	ds_read_b128 v[192:195], v235 offset:37888
	ds_read_b128 v[196:199], v235 offset:38912
	ds_read_b128 v[200:203], v235 offset:39936
	s_setprio 0
	global_load_lds_dwordx4 v144, s[0:1]
	s_mov_b32 m0, s81
	s_nop 0
	global_load_lds_dwordx4 v142, s[0:1]
	s_waitcnt vmcnt(10) lgkmcnt(8)
	s_setprio 1
	s_barrier
	s_waitcnt lgkmcnt(0)
	v_mfma_f32_16x16x32_bf16 v[136:139], v[100:103], v[172:175], v[136:139]
	v_mfma_f32_16x16x32_bf16 v[132:135], v[156:159], v[172:175], v[132:135]
	v_mfma_f32_16x16x32_bf16 v[128:131], v[100:103], v[180:183], v[128:131]
	v_mfma_f32_16x16x32_bf16 v[124:127], v[156:159], v[180:183], v[124:127]
	v_mfma_f32_16x16x32_bf16 v[120:123], v[100:103], v[188:191], v[120:123]
	v_mfma_f32_16x16x32_bf16 v[116:119], v[156:159], v[188:191], v[116:119]
	v_mfma_f32_16x16x32_bf16 v[112:115], v[100:103], v[196:199], v[112:115]
	v_mfma_f32_16x16x32_bf16 v[108:111], v[156:159], v[196:199], v[108:111]
	v_mfma_f32_16x16x32_bf16 v[136:139], v[104:107], v[176:179], v[136:139]
	v_mfma_f32_16x16x32_bf16 v[132:135], v[160:163], v[176:179], v[132:135]
	v_mfma_f32_16x16x32_bf16 v[128:131], v[104:107], v[184:187], v[128:131]
	v_mfma_f32_16x16x32_bf16 v[124:127], v[160:163], v[184:187], v[124:127]
	v_mfma_f32_16x16x32_bf16 v[120:123], v[104:107], v[192:195], v[120:123]
	v_mfma_f32_16x16x32_bf16 v[116:119], v[160:163], v[192:195], v[116:119]
	v_mfma_f32_16x16x32_bf16 v[112:115], v[104:107], v[200:203], v[112:115]
	v_mfma_f32_16x16x32_bf16 v[108:111], v[160:163], v[200:203], v[108:111]
	s_barrier
	s_add_i32 s25, 0, 0x1c000
	s_add_i32 s0, s24, s68
	v_add_u32_e32 v166, s25, v233
	v_lshl_add_u64 v[164:165], v[164:165], 0, s[12:13]
	s_mov_b32 m0, s0
	ds_read_b128 v[204:207], v166
	ds_read_b128 v[208:211], v166 offset:1024
	ds_read_b128 v[212:215], v166 offset:2048
	ds_read_b128 v[216:219], v166 offset:3072
	s_setprio 0
	global_load_lds_dwordx4 v[164:165], off
	v_lshl_add_u64 v[164:165], v[220:221], 0, s[12:13]
	s_add_i32 m0, s0, 0x2000
	s_nop 0
	global_load_lds_dwordx4 v[164:165], off
	s_waitcnt vmcnt(10)
	s_setprio 1
	s_barrier
	s_waitcnt lgkmcnt(0)
	v_mfma_f32_16x16x32_bf16 v[64:67], v[204:207], v[172:175], v[64:67]
	v_mfma_f32_16x16x32_bf16 v[60:63], v[212:215], v[172:175], v[60:63]
	v_mfma_f32_16x16x32_bf16 v[56:59], v[204:207], v[180:183], v[56:59]
	v_mfma_f32_16x16x32_bf16 v[52:55], v[212:215], v[180:183], v[52:55]
	v_mfma_f32_16x16x32_bf16 v[48:51], v[204:207], v[188:191], v[48:51]
	v_mfma_f32_16x16x32_bf16 v[44:47], v[212:215], v[188:191], v[44:47]
	v_mfma_f32_16x16x32_bf16 v[40:43], v[204:207], v[196:199], v[40:43]
	v_mfma_f32_16x16x32_bf16 v[36:39], v[212:215], v[196:199], v[36:39]
	v_mfma_f32_16x16x32_bf16 v[64:67], v[208:211], v[176:179], v[64:67]
	v_mfma_f32_16x16x32_bf16 v[60:63], v[216:219], v[176:179], v[60:63]
	v_mfma_f32_16x16x32_bf16 v[56:59], v[208:211], v[184:187], v[56:59]
	v_mfma_f32_16x16x32_bf16 v[52:55], v[216:219], v[184:187], v[52:55]
	v_mfma_f32_16x16x32_bf16 v[48:51], v[208:211], v[192:195], v[48:51]
	v_mfma_f32_16x16x32_bf16 v[44:47], v[216:219], v[192:195], v[44:47]
	v_mfma_f32_16x16x32_bf16 v[40:43], v[208:211], v[200:203], v[40:43]
	v_mfma_f32_16x16x32_bf16 v[36:39], v[216:219], v[200:203], v[36:39]
	s_barrier
	s_mov_b32 m0, s21
	v_lshl_add_u64 v[164:165], v[222:223], 0, s[12:13]
	ds_read_b128 v[172:175], v235 offset:49152
	ds_read_b128 v[176:179], v235 offset:50176
	ds_read_b128 v[180:183], v235 offset:51200
	ds_read_b128 v[184:187], v235 offset:52224
	ds_read_b128 v[188:191], v235 offset:53248
	ds_read_b128 v[192:195], v235 offset:54272
	ds_read_b128 v[196:199], v235 offset:55296
	ds_read_b128 v[200:203], v235 offset:56320
	s_setprio 0
	global_load_lds_dwordx4 v[164:165], off
	v_lshl_add_u64 v[164:165], v[224:225], 0, s[12:13]
	s_mov_b32 m0, s48
	s_nop 0
	global_load_lds_dwordx4 v[164:165], off
	s_waitcnt vmcnt(10)
	s_setprio 1
	s_barrier
	s_waitcnt lgkmcnt(0)
	v_mfma_f32_16x16x32_bf16 v[96:99], v[100:103], v[172:175], v[96:99]
	v_mfma_f32_16x16x32_bf16 v[92:95], v[156:159], v[172:175], v[92:95]
	v_mfma_f32_16x16x32_bf16 v[88:91], v[100:103], v[180:183], v[88:91]
	v_mfma_f32_16x16x32_bf16 v[84:87], v[156:159], v[180:183], v[84:87]
	v_mfma_f32_16x16x32_bf16 v[80:83], v[100:103], v[188:191], v[80:83]
	v_mfma_f32_16x16x32_bf16 v[76:79], v[156:159], v[188:191], v[76:79]
	v_mfma_f32_16x16x32_bf16 v[72:75], v[100:103], v[196:199], v[72:75]
	v_mfma_f32_16x16x32_bf16 v[68:71], v[156:159], v[196:199], v[68:71]
	v_mfma_f32_16x16x32_bf16 v[96:99], v[104:107], v[176:179], v[96:99]
	v_mfma_f32_16x16x32_bf16 v[92:95], v[160:163], v[176:179], v[92:95]
	v_mfma_f32_16x16x32_bf16 v[88:91], v[104:107], v[184:187], v[88:91]
	v_mfma_f32_16x16x32_bf16 v[84:87], v[160:163], v[184:187], v[84:87]
	v_mfma_f32_16x16x32_bf16 v[80:83], v[104:107], v[192:195], v[80:83]
	v_mfma_f32_16x16x32_bf16 v[76:79], v[160:163], v[192:195], v[76:79]
	v_mfma_f32_16x16x32_bf16 v[72:75], v[104:107], v[200:203], v[72:75]
	v_mfma_f32_16x16x32_bf16 v[68:71], v[160:163], v[200:203], v[68:71]
	s_barrier
	s_add_u32 s0, s28, 0xb0080
	s_addc_u32 s1, s29, 0
	s_add_i32 s24, s25, s68
	s_setprio 0
	s_mov_b32 m0, s24
	s_nop 0
	global_load_lds_dwordx4 v26, s[0:1]
	s_add_i32 m0, s24, 0x2000
	s_nop 0
	global_load_lds_dwordx4 v140, s[0:1]
	v_add_u32_e32 v160, 0x10000, v233
	ds_read_b128 v[100:103], v160
	ds_read_b128 v[104:107], v160 offset:1024
	ds_read_b128 v[156:159], v160 offset:2048
	ds_read_b128 v[160:163], v160 offset:3072
	s_add_i32 s52, s52, 2
	s_add_u32 s18, s18, 0x100
	s_addc_u32 s19, s19, 0
	s_mov_b64 s[24:25], s[26:27]
	s_cmp_gt_u32 s52, 41
	s_cbranch_scc1 .Lth__395
	s_add_u32 s26, s24, 0x100
	s_addc_u32 s27, s25, 0
	s_add_i32 s0, 0, 0x10000
	s_cmp_eq_u32 s52, 40
	s_cselect_b32 s31, s43, s27
	s_cselect_b32 s30, s42, s26
	s_cselect_b32 s29, s45, s19
	s_cselect_b32 s28, s44, s18
	s_cmp_gt_u32 s52, 41

.LBB0_479:
	s_add_i32 m0, s37, 0xc000
	ds_read_b128 v[158:161], v165
	ds_read_b128 v[172:175], v165 offset:1024
	ds_read_b128 v[176:179], v165 offset:2048
	ds_read_b128 v[180:183], v165 offset:3072
	ds_read_b128 v[184:187], v165 offset:4096
	ds_read_b128 v[188:191], v165 offset:5120
	ds_read_b128 v[192:195], v165 offset:6144
	ds_read_b128 v[196:199], v165 offset:7168
	global_load_lds_dwordx4 v146, s[22:23]
	v_lshl_add_u64 v[166:167], s[22:23], 0, v[148:149]
	s_add_i32 m0, s37, 0xe000
	s_nop 0
	global_load_lds_dwordx4 v[166:167], off
	s_waitcnt vmcnt(10) lgkmcnt(8)
	s_setprio 1
	s_barrier
	s_waitcnt lgkmcnt(0)
	v_mfma_f32_16x16x32_bf16 v[136:139], v[100:103], v[158:161], v[136:139]
	v_mfma_f32_16x16x32_bf16 v[132:135], v[150:153], v[158:161], v[132:135]
	v_mfma_f32_16x16x32_bf16 v[128:131], v[100:103], v[176:179], v[128:131]
	v_mfma_f32_16x16x32_bf16 v[124:127], v[150:153], v[176:179], v[124:127]
	v_mfma_f32_16x16x32_bf16 v[120:123], v[100:103], v[184:187], v[120:123]
	v_mfma_f32_16x16x32_bf16 v[116:119], v[150:153], v[184:187], v[116:119]
	v_mfma_f32_16x16x32_bf16 v[112:115], v[100:103], v[192:195], v[112:115]
	v_mfma_f32_16x16x32_bf16 v[108:111], v[150:153], v[192:195], v[108:111]
	v_mfma_f32_16x16x32_bf16 v[136:139], v[104:107], v[172:175], v[136:139]
	v_mfma_f32_16x16x32_bf16 v[132:135], v[154:157], v[172:175], v[132:135]
	v_mfma_f32_16x16x32_bf16 v[128:131], v[104:107], v[180:183], v[128:131]
	v_mfma_f32_16x16x32_bf16 v[124:127], v[154:157], v[180:183], v[124:127]
	v_mfma_f32_16x16x32_bf16 v[120:123], v[104:107], v[188:191], v[120:123]
	v_mfma_f32_16x16x32_bf16 v[116:119], v[154:157], v[188:191], v[116:119]
	v_mfma_f32_16x16x32_bf16 v[112:115], v[104:107], v[196:199], v[112:115]
	v_mfma_f32_16x16x32_bf16 v[108:111], v[154:157], v[196:199], v[108:111]
	s_barrier
	s_add_i32 s72, 0, 0x14000
	v_add_u32_e32 v166, s72, v163
	s_add_i32 s0, s69, s36
	ds_read_b128 v[200:203], v166
	ds_read_b128 v[204:207], v166 offset:1024
	ds_read_b128 v[208:211], v166 offset:2048
	ds_read_b128 v[212:215], v166 offset:3072
	v_lshl_add_u64 v[166:167], s[24:25], 0, v[26:27]
	s_mov_b32 m0, s0
	v_lshl_add_u64 v[168:169], s[24:25], 0, v[140:141]
	s_setprio 0
	global_load_lds_dwordx4 v[166:167], off
	s_add_i32 m0, s0, 0x2000
	s_nop 0
	global_load_lds_dwordx4 v[168:169], off
	s_waitcnt vmcnt(10)
	s_setprio 1
	s_barrier
	s_waitcnt lgkmcnt(0)
	v_mfma_f32_16x16x32_bf16 v[64:67], v[200:203], v[158:161], v[64:67]
	v_mfma_f32_16x16x32_bf16 v[60:63], v[208:211], v[158:161], v[60:63]
	v_mfma_f32_16x16x32_bf16 v[56:59], v[200:203], v[176:179], v[56:59]
	v_mfma_f32_16x16x32_bf16 v[52:55], v[208:211], v[176:179], v[52:55]
	v_mfma_f32_16x16x32_bf16 v[48:51], v[200:203], v[184:187], v[48:51]
	v_mfma_f32_16x16x32_bf16 v[44:47], v[208:211], v[184:187], v[44:47]
	v_mfma_f32_16x16x32_bf16 v[40:43], v[200:203], v[192:195], v[40:43]
	v_mfma_f32_16x16x32_bf16 v[36:39], v[208:211], v[192:195], v[36:39]
	v_mfma_f32_16x16x32_bf16 v[64:67], v[204:207], v[172:175], v[64:67]
	v_mfma_f32_16x16x32_bf16 v[60:63], v[212:215], v[172:175], v[60:63]
	v_mfma_f32_16x16x32_bf16 v[56:59], v[204:207], v[180:183], v[56:59]
	v_mfma_f32_16x16x32_bf16 v[52:55], v[212:215], v[180:183], v[52:55]
	v_mfma_f32_16x16x32_bf16 v[48:51], v[204:207], v[188:191], v[48:51]
	v_mfma_f32_16x16x32_bf16 v[44:47], v[212:215], v[188:191], v[44:47]
	v_mfma_f32_16x16x32_bf16 v[40:43], v[204:207], v[196:199], v[40:43]
	v_mfma_f32_16x16x32_bf16 v[36:39], v[212:215], v[196:199], v[36:39]
	s_barrier
	s_mov_b32 m0, s37
	v_lshl_add_u64 v[216:217], s[26:27], 0, v[144:145]
	ds_read_b128 v[158:161], v165 offset:16384
	ds_read_b128 v[172:175], v165 offset:17408
	ds_read_b128 v[176:179], v165 offset:18432
	ds_read_b128 v[180:183], v165 offset:19456
	ds_read_b128 v[184:187], v165 offset:20480
	ds_read_b128 v[188:191], v165 offset:21504
	ds_read_b128 v[192:195], v165 offset:22528
	ds_read_b128 v[196:199], v165 offset:23552
	s_setprio 0
	global_load_lds_dwordx4 v[216:217], off
	v_lshl_add_u64 v[218:219], s[26:27], 0, v[142:143]
	s_mov_b32 m0, s56
	s_nop 0
	global_load_lds_dwordx4 v[218:219], off
	s_waitcnt vmcnt(10)
	s_setprio 1
	s_barrier
	s_waitcnt lgkmcnt(0)
	v_mfma_f32_16x16x32_bf16 v[96:99], v[100:103], v[158:161], v[96:99]
	v_mfma_f32_16x16x32_bf16 v[92:95], v[150:153], v[158:161], v[92:95]
	v_mfma_f32_16x16x32_bf16 v[88:91], v[100:103], v[176:179], v[88:91]
	v_mfma_f32_16x16x32_bf16 v[84:87], v[150:153], v[176:179], v[84:87]
	v_mfma_f32_16x16x32_bf16 v[80:83], v[100:103], v[184:187], v[80:83]
	v_mfma_f32_16x16x32_bf16 v[76:79], v[150:153], v[184:187], v[76:79]
	v_mfma_f32_16x16x32_bf16 v[72:75], v[100:103], v[192:195], v[72:75]
	v_mfma_f32_16x16x32_bf16 v[68:71], v[150:153], v[192:195], v[68:71]
	v_mfma_f32_16x16x32_bf16 v[96:99], v[104:107], v[172:175], v[96:99]
	v_mfma_f32_16x16x32_bf16 v[92:95], v[154:157], v[172:175], v[92:95]
	v_mfma_f32_16x16x32_bf16 v[88:91], v[104:107], v[180:183], v[88:91]
	v_mfma_f32_16x16x32_bf16 v[84:87], v[154:157], v[180:183], v[84:87]
	v_mfma_f32_16x16x32_bf16 v[80:83], v[104:107], v[188:191], v[80:83]
	v_mfma_f32_16x16x32_bf16 v[76:79], v[154:157], v[188:191], v[76:79]
	v_mfma_f32_16x16x32_bf16 v[72:75], v[104:107], v[196:199], v[72:75]
	v_mfma_f32_16x16x32_bf16 v[68:71], v[154:157], v[196:199], v[68:71]
	s_barrier
	s_add_u32 s0, s24, 0x40000
	s_addc_u32 s1, s25, 0
	s_add_i32 s69, s72, s36
	s_setprio 0
	s_mov_b32 m0, s69
	s_nop 0
	global_load_lds_dwordx4 v26, s[0:1]
	s_add_i32 m0, s69, 0x2000
	s_nop 0
	global_load_lds_dwordx4 v140, s[0:1]
	v_add_u32_e32 v154, 0x18000, v163
	ds_read_b128 v[100:103], v154
	ds_read_b128 v[104:107], v154 offset:1024
	ds_read_b128 v[150:153], v154 offset:2048
	ds_read_b128 v[154:157], v154 offset:3072
	s_waitcnt vmcnt(10)
	s_setprio 1
	s_barrier
	v_mfma_f32_16x16x32_bf16 v[32:35], v[200:203], v[158:161], v[32:35]
	v_mfma_f32_16x16x32_bf16 v[28:31], v[208:211], v[158:161], v[28:31]
	v_mfma_f32_16x16x32_bf16 v[22:25], v[200:203], v[176:179], v[22:25]
	v_mfma_f32_16x16x32_bf16 v[18:21], v[208:211], v[176:179], v[18:21]
	v_mfma_f32_16x16x32_bf16 v[14:17], v[200:203], v[184:187], v[14:17]
	v_mfma_f32_16x16x32_bf16 v[10:13], v[208:211], v[184:187], v[10:13]
	v_mfma_f32_16x16x32_bf16 v[6:9], v[200:203], v[192:195], v[6:9]
	v_mfma_f32_16x16x32_bf16 v[2:5], v[208:211], v[192:195], v[2:5]
	v_mfma_f32_16x16x32_bf16 v[32:35], v[204:207], v[172:175], v[32:35]
	v_mfma_f32_16x16x32_bf16 v[28:31], v[212:215], v[172:175], v[28:31]
	v_mfma_f32_16x16x32_bf16 v[22:25], v[204:207], v[180:183], v[22:25]
	v_mfma_f32_16x16x32_bf16 v[18:21], v[212:215], v[180:183], v[18:21]
	v_mfma_f32_16x16x32_bf16 v[14:17], v[204:207], v[188:191], v[14:17]
	v_mfma_f32_16x16x32_bf16 v[10:13], v[212:215], v[188:191], v[10:13]
	v_mfma_f32_16x16x32_bf16 v[6:9], v[204:207], v[196:199], v[6:9]
	v_mfma_f32_16x16x32_bf16 v[2:5], v[212:215], v[196:199], v[2:5]
	s_barrier
	s_add_i32 s69, 0, 0x18000
	s_add_u32 s0, s26, 0x40000
	s_addc_u32 s1, s27, 0
	s_mov_b32 m0, s57
	ds_read_b128 v[158:161], v165 offset:32768
	ds_read_b128 v[172:175], v165 offset:33792
	ds_read_b128 v[176:179], v165 offset:34816
	ds_read_b128 v[180:183], v165 offset:35840
	ds_read_b128 v[184:187], v165 offset:36864
	ds_read_b128 v[188:191], v165 offset:37888
	ds_read_b128 v[192:195], v165 offset:38912
	ds_read_b128 v[196:199], v165 offset:39936
	s_setprio 0
	global_load_lds_dwordx4 v144, s[0:1]
	s_mov_b32 m0, s58
	s_nop 0
	global_load_lds_dwordx4 v142, s[0:1]
	s_waitcnt vmcnt(10) lgkmcnt(8)
	s_setprio 1
	s_barrier
	s_waitcnt lgkmcnt(0)
	v_mfma_f32_16x16x32_bf16 v[136:139], v[100:103], v[158:161], v[136:139]
	v_mfma_f32_16x16x32_bf16 v[132:135], v[150:153], v[158:161], v[132:135]
	v_mfma_f32_16x16x32_bf16 v[128:131], v[100:103], v[176:179], v[128:131]
	v_mfma_f32_16x16x32_bf16 v[124:127], v[150:153], v[176:179], v[124:127]
	v_mfma_f32_16x16x32_bf16 v[120:123], v[100:103], v[184:187], v[120:123]
	v_mfma_f32_16x16x32_bf16 v[116:119], v[150:153], v[184:187], v[116:119]
	v_mfma_f32_16x16x32_bf16 v[112:115], v[100:103], v[192:195], v[112:115]
	v_mfma_f32_16x16x32_bf16 v[108:111], v[150:153], v[192:195], v[108:111]
	v_mfma_f32_16x16x32_bf16 v[136:139], v[104:107], v[172:175], v[136:139]
	v_mfma_f32_16x16x32_bf16 v[132:135], v[154:157], v[172:175], v[132:135]
	v_mfma_f32_16x16x32_bf16 v[128:131], v[104:107], v[180:183], v[128:131]
	v_mfma_f32_16x16x32_bf16 v[124:127], v[154:157], v[180:183], v[124:127]
	v_mfma_f32_16x16x32_bf16 v[120:123], v[104:107], v[188:191], v[120:123]
	v_mfma_f32_16x16x32_bf16 v[116:119], v[154:157], v[188:191], v[116:119]
	v_mfma_f32_16x16x32_bf16 v[112:115], v[104:107], v[196:199], v[112:115]
	v_mfma_f32_16x16x32_bf16 v[108:111], v[154:157], v[196:199], v[108:111]
	s_barrier
	s_add_i32 s26, 0, 0x1c000
	s_add_i32 s0, s69, s36
	v_add_u32_e32 v212, s26, v163
	v_lshl_add_u64 v[166:167], v[166:167], 0, s[12:13]
	s_mov_b32 m0, s0
	ds_read_b128 v[200:203], v212
	ds_read_b128 v[204:207], v212 offset:1024
	ds_read_b128 v[208:211], v212 offset:2048
	ds_read_b128 v[212:215], v212 offset:3072
	s_setprio 0
	global_load_lds_dwordx4 v[166:167], off
	v_lshl_add_u64 v[166:167], v[168:169], 0, s[12:13]
	s_add_i32 m0, s0, 0x2000
	s_nop 0
	global_load_lds_dwordx4 v[166:167], off
	s_waitcnt vmcnt(10)
	s_setprio 1
	s_barrier
	s_waitcnt lgkmcnt(0)
	v_mfma_f32_16x16x32_bf16 v[64:67], v[200:203], v[158:161], v[64:67]
	v_mfma_f32_16x16x32_bf16 v[60:63], v[208:211], v[158:161], v[60:63]
	v_mfma_f32_16x16x32_bf16 v[56:59], v[200:203], v[176:179], v[56:59]
	v_mfma_f32_16x16x32_bf16 v[52:55], v[208:211], v[176:179], v[52:55]
	v_mfma_f32_16x16x32_bf16 v[48:51], v[200:203], v[184:187], v[48:51]
	v_mfma_f32_16x16x32_bf16 v[44:47], v[208:211], v[184:187], v[44:47]
	v_mfma_f32_16x16x32_bf16 v[40:43], v[200:203], v[192:195], v[40:43]
	v_mfma_f32_16x16x32_bf16 v[36:39], v[208:211], v[192:195], v[36:39]
	v_mfma_f32_16x16x32_bf16 v[64:67], v[204:207], v[172:175], v[64:67]
	v_mfma_f32_16x16x32_bf16 v[60:63], v[212:215], v[172:175], v[60:63]
	v_mfma_f32_16x16x32_bf16 v[56:59], v[204:207], v[180:183], v[56:59]
	v_mfma_f32_16x16x32_bf16 v[52:55], v[212:215], v[180:183], v[52:55]
	v_mfma_f32_16x16x32_bf16 v[48:51], v[204:207], v[188:191], v[48:51]
	v_mfma_f32_16x16x32_bf16 v[44:47], v[212:215], v[188:191], v[44:47]
	v_mfma_f32_16x16x32_bf16 v[40:43], v[204:207], v[196:199], v[40:43]
	v_mfma_f32_16x16x32_bf16 v[36:39], v[212:215], v[196:199], v[36:39]
	s_barrier
	s_mov_b32 m0, s28
	v_lshl_add_u64 v[166:167], v[216:217], 0, s[12:13]
	ds_read_b128 v[158:161], v165 offset:49152
	ds_read_b128 v[172:175], v165 offset:50176
	ds_read_b128 v[176:179], v165 offset:51200
	ds_read_b128 v[180:183], v165 offset:52224
	ds_read_b128 v[184:187], v165 offset:53248
	ds_read_b128 v[188:191], v165 offset:54272
	ds_read_b128 v[192:195], v165 offset:55296
	ds_read_b128 v[196:199], v165 offset:56320
	s_setprio 0
	global_load_lds_dwordx4 v[166:167], off
	v_lshl_add_u64 v[166:167], v[218:219], 0, s[12:13]
	s_mov_b32 m0, s29
	s_nop 0
	global_load_lds_dwordx4 v[166:167], off
	s_waitcnt vmcnt(10)
	s_setprio 1
	s_barrier
	s_waitcnt lgkmcnt(0)
	v_mfma_f32_16x16x32_bf16 v[96:99], v[100:103], v[158:161], v[96:99]
	v_mfma_f32_16x16x32_bf16 v[92:95], v[150:153], v[158:161], v[92:95]
	v_mfma_f32_16x16x32_bf16 v[88:91], v[100:103], v[176:179], v[88:91]
	v_mfma_f32_16x16x32_bf16 v[84:87], v[150:153], v[176:179], v[84:87]
	v_mfma_f32_16x16x32_bf16 v[80:83], v[100:103], v[184:187], v[80:83]
	v_mfma_f32_16x16x32_bf16 v[76:79], v[150:153], v[184:187], v[76:79]
	v_mfma_f32_16x16x32_bf16 v[72:75], v[100:103], v[192:195], v[72:75]
	v_mfma_f32_16x16x32_bf16 v[68:71], v[150:153], v[192:195], v[68:71]
	v_mfma_f32_16x16x32_bf16 v[96:99], v[104:107], v[172:175], v[96:99]
	v_mfma_f32_16x16x32_bf16 v[92:95], v[154:157], v[172:175], v[92:95]
	v_mfma_f32_16x16x32_bf16 v[88:91], v[104:107], v[180:183], v[88:91]
	v_mfma_f32_16x16x32_bf16 v[84:87], v[154:157], v[180:183], v[84:87]
	v_mfma_f32_16x16x32_bf16 v[80:83], v[104:107], v[188:191], v[80:83]
	v_mfma_f32_16x16x32_bf16 v[76:79], v[154:157], v[188:191], v[76:79]
	v_mfma_f32_16x16x32_bf16 v[72:75], v[104:107], v[196:199], v[72:75]
	v_mfma_f32_16x16x32_bf16 v[68:71], v[154:157], v[196:199], v[68:71]
	s_barrier
	s_add_u32 s0, s24, 0x40080
	s_addc_u32 s1, s25, 0
	s_add_i32 s24, s26, s36
	s_setprio 0
	s_mov_b32 m0, s24
	s_nop 0
	global_load_lds_dwordx4 v26, s[0:1]
	s_add_i32 m0, s24, 0x2000
	s_nop 0
	global_load_lds_dwordx4 v140, s[0:1]
	v_add_u32_e32 v154, 0x10000, v163
	ds_read_b128 v[100:103], v154
	ds_read_b128 v[104:107], v154 offset:1024
	ds_read_b128 v[150:153], v154 offset:2048
	ds_read_b128 v[154:157], v154 offset:3072
	s_add_i32 s68, s68, 2
	s_add_u32 s22, s22, 0x100
	s_addc_u32 s23, s23, 0
	s_add_u32 s51, s51, 0x100
	s_addc_u32 s59, s59, 0
	s_cmp_gt_u32 s68, 13
	s_cbranch_scc1 .Lth__479
	s_add_u32 s0, s22, 0xfffc0080
	s_addc_u32 s1, s23, -1
	s_add_i32 s69, 0, 0x10000
	s_cmp_eq_u32 s68, 12
	s_cselect_b32 s27, s35, s1
	s_cselect_b32 s26, s40, s0
	s_cselect_b32 s25, s41, s59
	s_cselect_b32 s24, s49, s51
	s_cmp_gt_u32 s68, 13

.LBB0_887:
	s_add_i32 m0, s58, 0xc000
	ds_read_b128 v[150:153], v193
	ds_read_b128 v[154:157], v193 offset:1024
	ds_read_b128 v[158:161], v193 offset:2048
	ds_read_b128 v[162:165], v193 offset:3072
	ds_read_b128 v[184:187], v193 offset:4096
	ds_read_b128 v[194:197], v193 offset:5120
	ds_read_b128 v[198:201], v193 offset:6144
	ds_read_b128 v[202:205], v193 offset:7168
	global_load_lds_dwordx4 v180, s[22:23]
	s_add_i32 m0, s58, 0xe000
	s_nop 0
	global_load_lds_dwordx4 v182, s[22:23]
	s_waitcnt vmcnt(10) lgkmcnt(8)
	s_setprio 1
	s_barrier
	s_waitcnt lgkmcnt(0)
	v_mfma_f32_16x16x32_bf16 v[130:133], v[134:137], v[150:153], v[130:133]
	v_mfma_f32_16x16x32_bf16 v[126:129], v[142:145], v[150:153], v[126:129]
	v_mfma_f32_16x16x32_bf16 v[122:125], v[134:137], v[158:161], v[122:125]
	v_mfma_f32_16x16x32_bf16 v[118:121], v[142:145], v[158:161], v[118:121]
	v_mfma_f32_16x16x32_bf16 v[114:117], v[134:137], v[184:187], v[114:117]
	v_mfma_f32_16x16x32_bf16 v[110:113], v[142:145], v[184:187], v[110:113]
	v_mfma_f32_16x16x32_bf16 v[106:109], v[134:137], v[198:201], v[106:109]
	v_mfma_f32_16x16x32_bf16 v[102:105], v[142:145], v[198:201], v[102:105]
	v_mfma_f32_16x16x32_bf16 v[130:133], v[138:141], v[154:157], v[130:133]
	v_mfma_f32_16x16x32_bf16 v[126:129], v[146:149], v[154:157], v[126:129]
	v_mfma_f32_16x16x32_bf16 v[122:125], v[138:141], v[162:165], v[122:125]
	v_mfma_f32_16x16x32_bf16 v[118:121], v[146:149], v[162:165], v[118:121]
	v_mfma_f32_16x16x32_bf16 v[114:117], v[138:141], v[194:197], v[114:117]
	v_mfma_f32_16x16x32_bf16 v[110:113], v[146:149], v[194:197], v[110:113]
	v_mfma_f32_16x16x32_bf16 v[106:109], v[138:141], v[202:205], v[106:109]
	v_mfma_f32_16x16x32_bf16 v[102:105], v[146:149], v[202:205], v[102:105]
	s_barrier
	s_add_i32 s22, 0, 0x14000
	s_add_i32 s0, s0, s55
	v_add_u32_e32 v26, s22, v191
	v_lshl_add_u64 v[166:167], s[26:27], 0, v[176:177]
	s_mov_b32 m0, s0
	ds_read_b128 v[206:209], v26
	ds_read_b128 v[210:213], v26 offset:1024
	ds_read_b128 v[214:217], v26 offset:2048
	ds_read_b128 v[218:221], v26 offset:3072
	s_setprio 0
	global_load_lds_dwordx4 v[166:167], off
	v_lshl_add_u64 v[168:169], s[26:27], 0, v[172:173]
	s_add_i32 m0, s0, 0x2000
	s_nop 0
	global_load_lds_dwordx4 v[168:169], off
	s_waitcnt vmcnt(10)
	s_setprio 1
	s_barrier
	s_waitcnt lgkmcnt(0)
	v_mfma_f32_16x16x32_bf16 v[98:101], v[206:209], v[150:153], v[98:101]
	v_mfma_f32_16x16x32_bf16 v[94:97], v[214:217], v[150:153], v[94:97]
	v_mfma_f32_16x16x32_bf16 v[90:93], v[206:209], v[158:161], v[90:93]
	v_mfma_f32_16x16x32_bf16 v[86:89], v[214:217], v[158:161], v[86:89]
	v_mfma_f32_16x16x32_bf16 v[82:85], v[206:209], v[184:187], v[82:85]
	v_mfma_f32_16x16x32_bf16 v[78:81], v[214:217], v[184:187], v[78:81]
	v_mfma_f32_16x16x32_bf16 v[74:77], v[206:209], v[198:201], v[74:77]
	v_mfma_f32_16x16x32_bf16 v[70:73], v[214:217], v[198:201], v[70:73]
	v_mfma_f32_16x16x32_bf16 v[98:101], v[210:213], v[154:157], v[98:101]
	v_mfma_f32_16x16x32_bf16 v[94:97], v[218:221], v[154:157], v[94:97]
	v_mfma_f32_16x16x32_bf16 v[90:93], v[210:213], v[162:165], v[90:93]
	v_mfma_f32_16x16x32_bf16 v[86:89], v[218:221], v[162:165], v[86:89]
	v_mfma_f32_16x16x32_bf16 v[82:85], v[210:213], v[194:197], v[82:85]
	v_mfma_f32_16x16x32_bf16 v[78:81], v[218:221], v[194:197], v[78:81]
	v_mfma_f32_16x16x32_bf16 v[74:77], v[210:213], v[202:205], v[74:77]
	v_mfma_f32_16x16x32_bf16 v[70:73], v[218:221], v[202:205], v[70:73]
	s_barrier
	s_mov_b32 m0, s58
	v_lshl_add_u64 v[188:189], s[28:29], 0, v[178:179]
	ds_read_b128 v[150:153], v193 offset:16384
	ds_read_b128 v[154:157], v193 offset:17408
	ds_read_b128 v[158:161], v193 offset:18432
	ds_read_b128 v[162:165], v193 offset:19456
	ds_read_b128 v[184:187], v193 offset:20480
	ds_read_b128 v[194:197], v193 offset:21504
	ds_read_b128 v[198:201], v193 offset:22528
	ds_read_b128 v[202:205], v193 offset:23552
	s_setprio 0
	global_load_lds_dwordx4 v[188:189], off
	v_lshl_add_u64 v[222:223], s[28:29], 0, v[174:175]
	s_mov_b32 m0, s59
	s_nop 0
	global_load_lds_dwordx4 v[222:223], off
	s_waitcnt vmcnt(10)
	s_setprio 1
	s_barrier
	s_waitcnt lgkmcnt(0)
	v_mfma_f32_16x16x32_bf16 v[66:69], v[134:137], v[150:153], v[66:69]
	v_mfma_f32_16x16x32_bf16 v[62:65], v[142:145], v[150:153], v[62:65]
	v_mfma_f32_16x16x32_bf16 v[58:61], v[134:137], v[158:161], v[58:61]
	v_mfma_f32_16x16x32_bf16 v[54:57], v[142:145], v[158:161], v[54:57]
	v_mfma_f32_16x16x32_bf16 v[50:53], v[134:137], v[184:187], v[50:53]
	v_mfma_f32_16x16x32_bf16 v[46:49], v[142:145], v[184:187], v[46:49]
	v_mfma_f32_16x16x32_bf16 v[42:45], v[134:137], v[198:201], v[42:45]
	v_mfma_f32_16x16x32_bf16 v[38:41], v[142:145], v[198:201], v[38:41]
	v_mfma_f32_16x16x32_bf16 v[66:69], v[138:141], v[154:157], v[66:69]
	v_mfma_f32_16x16x32_bf16 v[62:65], v[146:149], v[154:157], v[62:65]
	v_mfma_f32_16x16x32_bf16 v[58:61], v[138:141], v[162:165], v[58:61]
	v_mfma_f32_16x16x32_bf16 v[54:57], v[146:149], v[162:165], v[54:57]
	v_mfma_f32_16x16x32_bf16 v[50:53], v[138:141], v[194:197], v[50:53]
	v_mfma_f32_16x16x32_bf16 v[46:49], v[146:149], v[194:197], v[46:49]
	v_mfma_f32_16x16x32_bf16 v[42:45], v[138:141], v[202:205], v[42:45]
	v_mfma_f32_16x16x32_bf16 v[38:41], v[146:149], v[202:205], v[38:41]
	s_barrier
	s_add_u32 s0, s26, 0x20000
	s_addc_u32 s1, s27, 0
	s_add_i32 s22, s22, s55
	s_setprio 0
	s_mov_b32 m0, s22
	s_nop 0
	global_load_lds_dwordx4 v176, s[0:1]
	s_add_i32 m0, s22, 0x2000
	s_nop 0
	global_load_lds_dwordx4 v172, s[0:1]
	v_add_u32_e32 v26, 0x18000, v191
	ds_read_b128 v[134:137], v26
	ds_read_b128 v[138:141], v26 offset:1024
	ds_read_b128 v[142:145], v26 offset:2048
	ds_read_b128 v[146:149], v26 offset:3072
	s_waitcnt vmcnt(10)
	s_setprio 1
	s_barrier
	v_mfma_f32_16x16x32_bf16 v[34:37], v[206:209], v[150:153], v[34:37]
	v_mfma_f32_16x16x32_bf16 v[28:31], v[214:217], v[150:153], v[30:33]
	v_mfma_f32_16x16x32_bf16 v[22:25], v[206:209], v[158:161], v[22:25]
	v_mfma_f32_16x16x32_bf16 v[18:21], v[214:217], v[158:161], v[18:21]
	v_mfma_f32_16x16x32_bf16 v[14:17], v[206:209], v[184:187], v[14:17]
	v_mfma_f32_16x16x32_bf16 v[10:13], v[214:217], v[184:187], v[10:13]
	v_mfma_f32_16x16x32_bf16 v[6:9], v[206:209], v[198:201], v[6:9]
	v_mfma_f32_16x16x32_bf16 v[2:5], v[214:217], v[198:201], v[2:5]
	v_mfma_f32_16x16x32_bf16 v[34:37], v[210:213], v[154:157], v[34:37]
	v_mfma_f32_16x16x32_bf16 v[28:31], v[218:221], v[154:157], v[28:31]
	v_mfma_f32_16x16x32_bf16 v[22:25], v[210:213], v[162:165], v[22:25]
	v_mfma_f32_16x16x32_bf16 v[18:21], v[218:221], v[162:165], v[18:21]
	v_mfma_f32_16x16x32_bf16 v[14:17], v[210:213], v[194:197], v[14:17]
	v_mfma_f32_16x16x32_bf16 v[10:13], v[218:221], v[194:197], v[10:13]
	v_mfma_f32_16x16x32_bf16 v[6:9], v[210:213], v[202:205], v[6:9]
	v_mfma_f32_16x16x32_bf16 v[2:5], v[218:221], v[202:205], v[2:5]
	s_barrier
	s_add_i32 s22, 0, 0x18000
	s_add_u32 s0, s28, 0x140000
	s_addc_u32 s1, s29, 0
	s_mov_b32 m0, s68
	ds_read_b128 v[150:153], v193 offset:32768
	ds_read_b128 v[154:157], v193 offset:33792
	ds_read_b128 v[158:161], v193 offset:34816
	ds_read_b128 v[162:165], v193 offset:35840
	ds_read_b128 v[184:187], v193 offset:36864
	ds_read_b128 v[194:197], v193 offset:37888
	ds_read_b128 v[198:201], v193 offset:38912
	ds_read_b128 v[202:205], v193 offset:39936
	s_setprio 0
	global_load_lds_dwordx4 v178, s[0:1]
	s_mov_b32 m0, s69
	s_nop 0
	global_load_lds_dwordx4 v174, s[0:1]
	s_waitcnt vmcnt(10) lgkmcnt(8)
	s_setprio 1
	s_barrier
	s_waitcnt lgkmcnt(0)
	v_mfma_f32_16x16x32_bf16 v[130:133], v[134:137], v[150:153], v[130:133]
	v_mfma_f32_16x16x32_bf16 v[126:129], v[142:145], v[150:153], v[126:129]
	v_mfma_f32_16x16x32_bf16 v[122:125], v[134:137], v[158:161], v[122:125]
	v_mfma_f32_16x16x32_bf16 v[118:121], v[142:145], v[158:161], v[118:121]
	v_mfma_f32_16x16x32_bf16 v[114:117], v[134:137], v[184:187], v[114:117]
	v_mfma_f32_16x16x32_bf16 v[110:113], v[142:145], v[184:187], v[110:113]
	v_mfma_f32_16x16x32_bf16 v[106:109], v[134:137], v[198:201], v[106:109]
	v_mfma_f32_16x16x32_bf16 v[102:105], v[142:145], v[198:201], v[102:105]
	v_mfma_f32_16x16x32_bf16 v[130:133], v[138:141], v[154:157], v[130:133]
	v_mfma_f32_16x16x32_bf16 v[126:129], v[146:149], v[154:157], v[126:129]
	v_mfma_f32_16x16x32_bf16 v[122:125], v[138:141], v[162:165], v[122:125]
	v_mfma_f32_16x16x32_bf16 v[118:121], v[146:149], v[162:165], v[118:121]
	v_mfma_f32_16x16x32_bf16 v[114:117], v[138:141], v[194:197], v[114:117]
	v_mfma_f32_16x16x32_bf16 v[110:113], v[146:149], v[194:197], v[110:113]
	v_mfma_f32_16x16x32_bf16 v[106:109], v[138:141], v[202:205], v[106:109]
	v_mfma_f32_16x16x32_bf16 v[102:105], v[146:149], v[202:205], v[102:105]
	s_barrier
	s_add_i32 s23, 0, 0x1c000
	s_add_i32 s0, s22, s55
	v_add_u32_e32 v26, s23, v191
	v_lshl_add_u64 v[32:33], v[166:167], 0, s[12:13]
	s_mov_b32 m0, s0
	ds_read_b128 v[206:209], v26
	ds_read_b128 v[210:213], v26 offset:1024
	ds_read_b128 v[214:217], v26 offset:2048
	ds_read_b128 v[218:221], v26 offset:3072
	s_setprio 0
	global_load_lds_dwordx4 v[32:33], off
	v_lshl_add_u64 v[32:33], v[168:169], 0, s[12:13]
	s_add_i32 m0, s0, 0x2000
	s_nop 0
	global_load_lds_dwordx4 v[32:33], off
	s_waitcnt vmcnt(10)
	s_setprio 1
	s_barrier
	s_waitcnt lgkmcnt(0)
	v_mfma_f32_16x16x32_bf16 v[98:101], v[206:209], v[150:153], v[98:101]
	v_mfma_f32_16x16x32_bf16 v[94:97], v[214:217], v[150:153], v[94:97]
	v_mfma_f32_16x16x32_bf16 v[90:93], v[206:209], v[158:161], v[90:93]
	v_mfma_f32_16x16x32_bf16 v[86:89], v[214:217], v[158:161], v[86:89]
	v_mfma_f32_16x16x32_bf16 v[82:85], v[206:209], v[184:187], v[82:85]
	v_mfma_f32_16x16x32_bf16 v[78:81], v[214:217], v[184:187], v[78:81]
	v_mfma_f32_16x16x32_bf16 v[74:77], v[206:209], v[198:201], v[74:77]
	v_mfma_f32_16x16x32_bf16 v[70:73], v[214:217], v[198:201], v[70:73]
	v_mfma_f32_16x16x32_bf16 v[98:101], v[210:213], v[154:157], v[98:101]
	v_mfma_f32_16x16x32_bf16 v[94:97], v[218:221], v[154:157], v[94:97]
	v_mfma_f32_16x16x32_bf16 v[90:93], v[210:213], v[162:165], v[90:93]
	v_mfma_f32_16x16x32_bf16 v[86:89], v[218:221], v[162:165], v[86:89]
	v_mfma_f32_16x16x32_bf16 v[82:85], v[210:213], v[194:197], v[82:85]
	v_mfma_f32_16x16x32_bf16 v[78:81], v[218:221], v[194:197], v[78:81]
	v_mfma_f32_16x16x32_bf16 v[74:77], v[210:213], v[202:205], v[74:77]
	v_mfma_f32_16x16x32_bf16 v[70:73], v[218:221], v[202:205], v[70:73]
	s_barrier
	s_mov_b32 m0, s30
	v_lshl_add_u64 v[32:33], v[188:189], 0, s[12:13]
	ds_read_b128 v[150:153], v193 offset:49152
	ds_read_b128 v[154:157], v193 offset:50176
	ds_read_b128 v[158:161], v193 offset:51200
	ds_read_b128 v[162:165], v193 offset:52224
	ds_read_b128 v[184:187], v193 offset:53248
	ds_read_b128 v[194:197], v193 offset:54272
	ds_read_b128 v[198:201], v193 offset:55296
	ds_read_b128 v[202:205], v193 offset:56320
	s_setprio 0
	global_load_lds_dwordx4 v[32:33], off
	v_lshl_add_u64 v[32:33], v[222:223], 0, s[12:13]
	s_mov_b32 m0, s34
	s_nop 0
	global_load_lds_dwordx4 v[32:33], off
	s_waitcnt vmcnt(10)
	s_setprio 1
	s_barrier
	s_waitcnt lgkmcnt(0)
	v_mfma_f32_16x16x32_bf16 v[66:69], v[134:137], v[150:153], v[66:69]
	v_mfma_f32_16x16x32_bf16 v[62:65], v[142:145], v[150:153], v[62:65]
	v_mfma_f32_16x16x32_bf16 v[58:61], v[134:137], v[158:161], v[58:61]
	v_mfma_f32_16x16x32_bf16 v[54:57], v[142:145], v[158:161], v[54:57]
	v_mfma_f32_16x16x32_bf16 v[50:53], v[134:137], v[184:187], v[50:53]
	v_mfma_f32_16x16x32_bf16 v[46:49], v[142:145], v[184:187], v[46:49]
	v_mfma_f32_16x16x32_bf16 v[42:45], v[134:137], v[198:201], v[42:45]
	v_mfma_f32_16x16x32_bf16 v[38:41], v[142:145], v[198:201], v[38:41]
	v_mfma_f32_16x16x32_bf16 v[66:69], v[138:141], v[154:157], v[66:69]
	v_mfma_f32_16x16x32_bf16 v[62:65], v[146:149], v[154:157], v[62:65]
	v_mfma_f32_16x16x32_bf16 v[58:61], v[138:141], v[162:165], v[58:61]
	v_mfma_f32_16x16x32_bf16 v[54:57], v[146:149], v[162:165], v[54:57]
	v_mfma_f32_16x16x32_bf16 v[50:53], v[138:141], v[194:197], v[50:53]
	v_mfma_f32_16x16x32_bf16 v[46:49], v[146:149], v[194:197], v[46:49]
	v_mfma_f32_16x16x32_bf16 v[42:45], v[138:141], v[202:205], v[42:45]
	v_mfma_f32_16x16x32_bf16 v[38:41], v[146:149], v[202:205], v[38:41]
	s_barrier
	s_add_u32 s0, s26, 0x20080
	s_addc_u32 s1, s27, 0
	s_add_i32 s22, s23, s55
	s_setprio 0
	s_mov_b32 m0, s22
	s_nop 0
	global_load_lds_dwordx4 v176, s[0:1]
	s_add_i32 m0, s22, 0x2000
	s_nop 0
	global_load_lds_dwordx4 v172, s[0:1]
	v_add_u32_e32 v26, 0x10000, v191
	ds_read_b128 v[134:137], v26
	ds_read_b128 v[138:141], v26 offset:1024
	ds_read_b128 v[142:145], v26 offset:2048
	ds_read_b128 v[146:149], v26 offset:3072
	s_add_i32 s51, s51, 2
	s_add_u32 s45, s45, 0x100
	s_addc_u32 s50, s50, 0
	s_mov_b64 s[22:23], s[24:25]
	s_cmp_gt_u32 s51, 5
	s_cbranch_scc1 .Lth__887
	s_add_u32 s24, s22, 0x100
	s_addc_u32 s25, s23, 0
	s_add_i32 s0, 0, 0x10000
	s_cmp_eq_u32 s51, 4
	s_cselect_b32 s29, s47, s25
	s_cselect_b32 s28, s46, s24
	s_cselect_b32 s27, s18, s50
	s_cselect_b32 s26, s19, s45
	s_cmp_gt_u32 s51, 5

.LBB0_965:
	s_add_i32 m0, s54, 0xc000
	ds_read_b128 v[148:151], v224
	ds_read_b128 v[152:155], v224 offset:1024
	ds_read_b128 v[178:181], v224 offset:2048
	ds_read_b128 v[182:185], v224 offset:3072
	ds_read_b128 v[186:189], v224 offset:4096
	ds_read_b128 v[190:193], v224 offset:5120
	ds_read_b128 v[194:197], v224 offset:6144
	ds_read_b128 v[198:201], v224 offset:7168
	global_load_lds_dwordx4 v174, s[34:35]
	v_lshl_add_u64 v[166:167], s[34:35], 0, v[176:177]
	s_add_i32 m0, s54, 0xe000
	s_nop 0
	global_load_lds_dwordx4 v[166:167], off
	s_waitcnt vmcnt(10) lgkmcnt(8)
	s_setprio 1
	s_barrier
	s_waitcnt lgkmcnt(0)
	v_mfma_f32_16x16x32_bf16 v[136:139], v[100:103], v[148:151], v[136:139]
	v_mfma_f32_16x16x32_bf16 v[132:135], v[140:143], v[148:151], v[132:135]
	v_mfma_f32_16x16x32_bf16 v[128:131], v[100:103], v[178:181], v[128:131]
	v_mfma_f32_16x16x32_bf16 v[124:127], v[140:143], v[178:181], v[124:127]
	v_mfma_f32_16x16x32_bf16 v[120:123], v[100:103], v[186:189], v[120:123]
	v_mfma_f32_16x16x32_bf16 v[116:119], v[140:143], v[186:189], v[116:119]
	v_mfma_f32_16x16x32_bf16 v[112:115], v[100:103], v[194:197], v[112:115]
	v_mfma_f32_16x16x32_bf16 v[108:111], v[140:143], v[194:197], v[108:111]
	v_mfma_f32_16x16x32_bf16 v[136:139], v[104:107], v[152:155], v[136:139]
	v_mfma_f32_16x16x32_bf16 v[132:135], v[144:147], v[152:155], v[132:135]
	v_mfma_f32_16x16x32_bf16 v[128:131], v[104:107], v[182:185], v[128:131]
	v_mfma_f32_16x16x32_bf16 v[124:127], v[144:147], v[182:185], v[124:127]
	v_mfma_f32_16x16x32_bf16 v[120:123], v[104:107], v[190:193], v[120:123]
	v_mfma_f32_16x16x32_bf16 v[116:119], v[144:147], v[190:193], v[116:119]
	v_mfma_f32_16x16x32_bf16 v[112:115], v[104:107], v[198:201], v[112:115]
	v_mfma_f32_16x16x32_bf16 v[108:111], v[144:147], v[198:201], v[108:111]
	s_barrier
	s_add_i32 s34, 0, 0x14000
	v_add_u32_e32 v166, s34, v222
	s_add_i32 s0, s0, s53
	ds_read_b128 v[202:205], v166
	ds_read_b128 v[206:209], v166 offset:1024
	ds_read_b128 v[210:213], v166 offset:2048
	ds_read_b128 v[214:217], v166 offset:3072
	v_lshl_add_u64 v[166:167], s[42:43], 0, v[26:27]
	s_mov_b32 m0, s0
	v_lshl_add_u64 v[168:169], s[42:43], 0, v[160:161]
	s_setprio 0
	global_load_lds_dwordx4 v[166:167], off
	s_add_i32 m0, s0, 0x2000
	s_nop 0
	global_load_lds_dwordx4 v[168:169], off
	s_waitcnt vmcnt(10)
	s_setprio 1
	s_barrier
	s_waitcnt lgkmcnt(0)
	v_mfma_f32_16x16x32_bf16 v[64:67], v[202:205], v[148:151], v[64:67]
	v_mfma_f32_16x16x32_bf16 v[60:63], v[210:213], v[148:151], v[60:63]
	v_mfma_f32_16x16x32_bf16 v[56:59], v[202:205], v[178:181], v[56:59]
	v_mfma_f32_16x16x32_bf16 v[52:55], v[210:213], v[178:181], v[52:55]
	v_mfma_f32_16x16x32_bf16 v[48:51], v[202:205], v[186:189], v[48:51]
	v_mfma_f32_16x16x32_bf16 v[44:47], v[210:213], v[186:189], v[44:47]
	v_mfma_f32_16x16x32_bf16 v[40:43], v[202:205], v[194:197], v[40:43]
	v_mfma_f32_16x16x32_bf16 v[36:39], v[210:213], v[194:197], v[36:39]
	v_mfma_f32_16x16x32_bf16 v[64:67], v[206:209], v[152:155], v[64:67]
	v_mfma_f32_16x16x32_bf16 v[60:63], v[214:217], v[152:155], v[60:63]
	v_mfma_f32_16x16x32_bf16 v[56:59], v[206:209], v[182:185], v[56:59]
	v_mfma_f32_16x16x32_bf16 v[52:55], v[214:217], v[182:185], v[52:55]
	v_mfma_f32_16x16x32_bf16 v[48:51], v[206:209], v[190:193], v[48:51]
	v_mfma_f32_16x16x32_bf16 v[44:47], v[214:217], v[190:193], v[44:47]
	v_mfma_f32_16x16x32_bf16 v[40:43], v[206:209], v[198:201], v[40:43]
	v_mfma_f32_16x16x32_bf16 v[36:39], v[214:217], v[198:201], v[36:39]
	s_barrier
	s_mov_b32 m0, s54
	v_lshl_add_u64 v[218:219], s[46:47], 0, v[156:157]
	ds_read_b128 v[148:151], v224 offset:16384
	ds_read_b128 v[152:155], v224 offset:17408
	ds_read_b128 v[178:181], v224 offset:18432
	ds_read_b128 v[182:185], v224 offset:19456
	ds_read_b128 v[186:189], v224 offset:20480
	ds_read_b128 v[190:193], v224 offset:21504
	ds_read_b128 v[194:197], v224 offset:22528
	ds_read_b128 v[198:201], v224 offset:23552
	s_setprio 0
	global_load_lds_dwordx4 v[218:219], off
	v_lshl_add_u64 v[220:221], s[46:47], 0, v[158:159]
	s_mov_b32 m0, s55
	s_nop 0
	global_load_lds_dwordx4 v[220:221], off
	s_waitcnt vmcnt(10)
	s_setprio 1
	s_barrier
	s_waitcnt lgkmcnt(0)
	v_mfma_f32_16x16x32_bf16 v[96:99], v[100:103], v[148:151], v[96:99]
	v_mfma_f32_16x16x32_bf16 v[92:95], v[140:143], v[148:151], v[92:95]
	v_mfma_f32_16x16x32_bf16 v[88:91], v[100:103], v[178:181], v[88:91]
	v_mfma_f32_16x16x32_bf16 v[84:87], v[140:143], v[178:181], v[84:87]
	v_mfma_f32_16x16x32_bf16 v[80:83], v[100:103], v[186:189], v[80:83]
	v_mfma_f32_16x16x32_bf16 v[76:79], v[140:143], v[186:189], v[76:79]
	v_mfma_f32_16x16x32_bf16 v[72:75], v[100:103], v[194:197], v[72:75]
	v_mfma_f32_16x16x32_bf16 v[68:71], v[140:143], v[194:197], v[68:71]
	v_mfma_f32_16x16x32_bf16 v[96:99], v[104:107], v[152:155], v[96:99]
	v_mfma_f32_16x16x32_bf16 v[92:95], v[144:147], v[152:155], v[92:95]
	v_mfma_f32_16x16x32_bf16 v[88:91], v[104:107], v[182:185], v[88:91]
	v_mfma_f32_16x16x32_bf16 v[84:87], v[144:147], v[182:185], v[84:87]
	v_mfma_f32_16x16x32_bf16 v[80:83], v[104:107], v[190:193], v[80:83]
	v_mfma_f32_16x16x32_bf16 v[76:79], v[144:147], v[190:193], v[76:79]
	v_mfma_f32_16x16x32_bf16 v[72:75], v[104:107], v[198:201], v[72:75]
	v_mfma_f32_16x16x32_bf16 v[68:71], v[144:147], v[198:201], v[68:71]
	s_barrier
	s_add_u32 s0, s42, 0x40000
	s_addc_u32 s1, s43, 0
	s_add_i32 s34, s34, s53
	s_setprio 0
	s_mov_b32 m0, s34
	s_nop 0
	global_load_lds_dwordx4 v26, s[0:1]
	s_add_i32 m0, s34, 0x2000
	s_nop 0
	global_load_lds_dwordx4 v160, s[0:1]
	v_add_u32_e32 v144, 0x18000, v222
	ds_read_b128 v[100:103], v144
	ds_read_b128 v[104:107], v144 offset:1024
	ds_read_b128 v[140:143], v144 offset:2048
	ds_read_b128 v[144:147], v144 offset:3072
	s_waitcnt vmcnt(10)
	s_setprio 1
	s_barrier
	v_mfma_f32_16x16x32_bf16 v[32:35], v[202:205], v[148:151], v[32:35]
	v_mfma_f32_16x16x32_bf16 v[28:31], v[210:213], v[148:151], v[28:31]
	v_mfma_f32_16x16x32_bf16 v[22:25], v[202:205], v[178:181], v[22:25]
	v_mfma_f32_16x16x32_bf16 v[18:21], v[210:213], v[178:181], v[18:21]
	v_mfma_f32_16x16x32_bf16 v[14:17], v[202:205], v[186:189], v[14:17]
	v_mfma_f32_16x16x32_bf16 v[10:13], v[210:213], v[186:189], v[10:13]
	v_mfma_f32_16x16x32_bf16 v[6:9], v[202:205], v[194:197], v[6:9]
	v_mfma_f32_16x16x32_bf16 v[2:5], v[210:213], v[194:197], v[2:5]
	v_mfma_f32_16x16x32_bf16 v[32:35], v[206:209], v[152:155], v[32:35]
	v_mfma_f32_16x16x32_bf16 v[28:31], v[214:217], v[152:155], v[28:31]
	v_mfma_f32_16x16x32_bf16 v[22:25], v[206:209], v[182:185], v[22:25]
	v_mfma_f32_16x16x32_bf16 v[18:21], v[214:217], v[182:185], v[18:21]
	v_mfma_f32_16x16x32_bf16 v[14:17], v[206:209], v[190:193], v[14:17]
	v_mfma_f32_16x16x32_bf16 v[10:13], v[214:217], v[190:193], v[10:13]
	v_mfma_f32_16x16x32_bf16 v[6:9], v[206:209], v[198:201], v[6:9]
	v_mfma_f32_16x16x32_bf16 v[2:5], v[214:217], v[198:201], v[2:5]
	s_barrier
	s_add_i32 s34, 0, 0x18000
	s_add_u32 s0, s46, 0x140000
	s_addc_u32 s1, s47, 0
	s_mov_b32 m0, s56
	ds_read_b128 v[148:151], v224 offset:32768
	ds_read_b128 v[152:155], v224 offset:33792
	ds_read_b128 v[178:181], v224 offset:34816
	ds_read_b128 v[182:185], v224 offset:35840
	ds_read_b128 v[186:189], v224 offset:36864
	ds_read_b128 v[190:193], v224 offset:37888
	ds_read_b128 v[194:197], v224 offset:38912
	ds_read_b128 v[198:201], v224 offset:39936
	s_setprio 0
	global_load_lds_dwordx4 v156, s[0:1]
	s_mov_b32 m0, s57
	s_nop 0
	global_load_lds_dwordx4 v158, s[0:1]
	s_waitcnt vmcnt(10) lgkmcnt(8)
	s_setprio 1
	s_barrier
	s_waitcnt lgkmcnt(0)
	v_mfma_f32_16x16x32_bf16 v[136:139], v[100:103], v[148:151], v[136:139]
	v_mfma_f32_16x16x32_bf16 v[132:135], v[140:143], v[148:151], v[132:135]
	v_mfma_f32_16x16x32_bf16 v[128:131], v[100:103], v[178:181], v[128:131]
	v_mfma_f32_16x16x32_bf16 v[124:127], v[140:143], v[178:181], v[124:127]
	v_mfma_f32_16x16x32_bf16 v[120:123], v[100:103], v[186:189], v[120:123]
	v_mfma_f32_16x16x32_bf16 v[116:119], v[140:143], v[186:189], v[116:119]
	v_mfma_f32_16x16x32_bf16 v[112:115], v[100:103], v[194:197], v[112:115]
	v_mfma_f32_16x16x32_bf16 v[108:111], v[140:143], v[194:197], v[108:111]
	v_mfma_f32_16x16x32_bf16 v[136:139], v[104:107], v[152:155], v[136:139]
	v_mfma_f32_16x16x32_bf16 v[132:135], v[144:147], v[152:155], v[132:135]
	v_mfma_f32_16x16x32_bf16 v[128:131], v[104:107], v[182:185], v[128:131]
	v_mfma_f32_16x16x32_bf16 v[124:127], v[144:147], v[182:185], v[124:127]
	v_mfma_f32_16x16x32_bf16 v[120:123], v[104:107], v[190:193], v[120:123]
	v_mfma_f32_16x16x32_bf16 v[116:119], v[144:147], v[190:193], v[116:119]
	v_mfma_f32_16x16x32_bf16 v[112:115], v[104:107], v[198:201], v[112:115]
	v_mfma_f32_16x16x32_bf16 v[108:111], v[144:147], v[198:201], v[108:111]
	s_barrier
	s_add_i32 s35, 0, 0x1c000
	s_add_i32 s0, s34, s53
	v_add_u32_e32 v214, s35, v222
	v_lshl_add_u64 v[166:167], v[166:167], 0, s[12:13]
	s_mov_b32 m0, s0
	ds_read_b128 v[202:205], v214
	ds_read_b128 v[206:209], v214 offset:1024
	ds_read_b128 v[210:213], v214 offset:2048
	ds_read_b128 v[214:217], v214 offset:3072
	s_setprio 0
	global_load_lds_dwordx4 v[166:167], off
	v_lshl_add_u64 v[166:167], v[168:169], 0, s[12:13]
	s_add_i32 m0, s0, 0x2000
	s_nop 0
	global_load_lds_dwordx4 v[166:167], off
	s_waitcnt vmcnt(10)
	s_setprio 1
	s_barrier
	s_waitcnt lgkmcnt(0)
	v_mfma_f32_16x16x32_bf16 v[64:67], v[202:205], v[148:151], v[64:67]
	v_mfma_f32_16x16x32_bf16 v[60:63], v[210:213], v[148:151], v[60:63]
	v_mfma_f32_16x16x32_bf16 v[56:59], v[202:205], v[178:181], v[56:59]
	v_mfma_f32_16x16x32_bf16 v[52:55], v[210:213], v[178:181], v[52:55]
	v_mfma_f32_16x16x32_bf16 v[48:51], v[202:205], v[186:189], v[48:51]
	v_mfma_f32_16x16x32_bf16 v[44:47], v[210:213], v[186:189], v[44:47]
	v_mfma_f32_16x16x32_bf16 v[40:43], v[202:205], v[194:197], v[40:43]
	v_mfma_f32_16x16x32_bf16 v[36:39], v[210:213], v[194:197], v[36:39]
	v_mfma_f32_16x16x32_bf16 v[64:67], v[206:209], v[152:155], v[64:67]
	v_mfma_f32_16x16x32_bf16 v[60:63], v[214:217], v[152:155], v[60:63]
	v_mfma_f32_16x16x32_bf16 v[56:59], v[206:209], v[182:185], v[56:59]
	v_mfma_f32_16x16x32_bf16 v[52:55], v[214:217], v[182:185], v[52:55]
	v_mfma_f32_16x16x32_bf16 v[48:51], v[206:209], v[190:193], v[48:51]
	v_mfma_f32_16x16x32_bf16 v[44:47], v[214:217], v[190:193], v[44:47]
	v_mfma_f32_16x16x32_bf16 v[40:43], v[206:209], v[198:201], v[40:43]
	v_mfma_f32_16x16x32_bf16 v[36:39], v[214:217], v[198:201], v[36:39]
	s_barrier
	s_mov_b32 m0, s81
	v_lshl_add_u64 v[166:167], v[218:219], 0, s[12:13]
	ds_read_b128 v[148:151], v224 offset:49152
	ds_read_b128 v[152:155], v224 offset:50176
	ds_read_b128 v[178:181], v224 offset:51200
	ds_read_b128 v[182:185], v224 offset:52224
	ds_read_b128 v[186:189], v224 offset:53248
	ds_read_b128 v[190:193], v224 offset:54272
	ds_read_b128 v[194:197], v224 offset:55296
	ds_read_b128 v[198:201], v224 offset:56320
	s_setprio 0
	global_load_lds_dwordx4 v[166:167], off
	v_lshl_add_u64 v[166:167], v[220:221], 0, s[12:13]
	s_mov_b32 m0, s17
	s_nop 0
	global_load_lds_dwordx4 v[166:167], off
	s_waitcnt vmcnt(10)
	s_setprio 1
	s_barrier
	s_waitcnt lgkmcnt(0)
	v_mfma_f32_16x16x32_bf16 v[96:99], v[100:103], v[148:151], v[96:99]
	v_mfma_f32_16x16x32_bf16 v[92:95], v[140:143], v[148:151], v[92:95]
	v_mfma_f32_16x16x32_bf16 v[88:91], v[100:103], v[178:181], v[88:91]
	v_mfma_f32_16x16x32_bf16 v[84:87], v[140:143], v[178:181], v[84:87]
	v_mfma_f32_16x16x32_bf16 v[80:83], v[100:103], v[186:189], v[80:83]
	v_mfma_f32_16x16x32_bf16 v[76:79], v[140:143], v[186:189], v[76:79]
	v_mfma_f32_16x16x32_bf16 v[72:75], v[100:103], v[194:197], v[72:75]
	v_mfma_f32_16x16x32_bf16 v[68:71], v[140:143], v[194:197], v[68:71]
	v_mfma_f32_16x16x32_bf16 v[96:99], v[104:107], v[152:155], v[96:99]
	v_mfma_f32_16x16x32_bf16 v[92:95], v[144:147], v[152:155], v[92:95]
	v_mfma_f32_16x16x32_bf16 v[88:91], v[104:107], v[182:185], v[88:91]
	v_mfma_f32_16x16x32_bf16 v[84:87], v[144:147], v[182:185], v[84:87]
	v_mfma_f32_16x16x32_bf16 v[80:83], v[104:107], v[190:193], v[80:83]
	v_mfma_f32_16x16x32_bf16 v[76:79], v[144:147], v[190:193], v[76:79]
	v_mfma_f32_16x16x32_bf16 v[72:75], v[104:107], v[198:201], v[72:75]
	v_mfma_f32_16x16x32_bf16 v[68:71], v[144:147], v[198:201], v[68:71]
	s_barrier
	s_add_u32 s0, s42, 0x40080
	s_addc_u32 s1, s43, 0
	s_add_i32 s34, s35, s53
	s_setprio 0
	s_mov_b32 m0, s34
	s_nop 0
	global_load_lds_dwordx4 v26, s[0:1]
	s_add_i32 m0, s34, 0x2000
	s_nop 0
	global_load_lds_dwordx4 v160, s[0:1]
	v_add_u32_e32 v144, 0x10000, v222
	ds_read_b128 v[100:103], v144
	ds_read_b128 v[104:107], v144 offset:1024
	ds_read_b128 v[140:143], v144 offset:2048
	ds_read_b128 v[144:147], v144 offset:3072
	s_add_i32 s31, s31, 2
	s_add_u32 s23, s23, 0x100
	s_addc_u32 s29, s29, 0
	s_mov_b64 s[34:35], s[36:37]
	s_cmp_gt_u32 s31, 13
	s_cbranch_scc1 .Lth__965
	s_add_u32 s36, s34, 0x100
	s_addc_u32 s37, s35, 0
	s_add_i32 s0, 0, 0x10000
	s_cmp_eq_u32 s31, 12
	s_cselect_b32 s47, s25, s37
	s_cselect_b32 s46, s24, s36
	s_cselect_b32 s43, s18, s29
	s_cselect_b32 s42, s19, s23
	s_cmp_gt_u32 s31, 13

.LBB0_1048:
	s_add_i32 m0, s23, 0xc000
	ds_read_b128 v[158:161], v165
	ds_read_b128 v[174:177], v165 offset:1024
	ds_read_b128 v[178:181], v165 offset:2048
	ds_read_b128 v[182:185], v165 offset:3072
	ds_read_b128 v[186:189], v165 offset:4096
	ds_read_b128 v[190:193], v165 offset:5120
	ds_read_b128 v[194:197], v165 offset:6144
	ds_read_b128 v[198:201], v165 offset:7168
	global_load_lds_dwordx4 v154, s[24:25]
	v_lshl_add_u64 v[166:167], s[24:25], 0, v[156:157]
	s_add_i32 m0, s23, 0xe000
	s_nop 0
	global_load_lds_dwordx4 v[166:167], off
	s_waitcnt vmcnt(10) lgkmcnt(8)
	s_setprio 1
	s_barrier
	s_waitcnt lgkmcnt(0)
	v_mfma_f32_16x16x32_bf16 v[144:147], v[68:71], v[158:161], v[144:147]
	v_mfma_f32_16x16x32_bf16 v[140:143], v[76:79], v[158:161], v[140:143]
	v_mfma_f32_16x16x32_bf16 v[128:131], v[68:71], v[178:181], v[128:131]
	v_mfma_f32_16x16x32_bf16 v[124:127], v[76:79], v[178:181], v[124:127]
	v_mfma_f32_16x16x32_bf16 v[112:115], v[68:71], v[186:189], v[112:115]
	v_mfma_f32_16x16x32_bf16 v[108:111], v[76:79], v[186:189], v[108:111]
	v_mfma_f32_16x16x32_bf16 v[96:99], v[68:71], v[194:197], v[96:99]
	v_mfma_f32_16x16x32_bf16 v[92:95], v[76:79], v[194:197], v[92:95]
	v_mfma_f32_16x16x32_bf16 v[144:147], v[72:75], v[174:177], v[144:147]
	v_mfma_f32_16x16x32_bf16 v[140:143], v[80:83], v[174:177], v[140:143]
	v_mfma_f32_16x16x32_bf16 v[128:131], v[72:75], v[182:185], v[128:131]
	v_mfma_f32_16x16x32_bf16 v[124:127], v[80:83], v[182:185], v[124:127]
	v_mfma_f32_16x16x32_bf16 v[112:115], v[72:75], v[190:193], v[112:115]
	v_mfma_f32_16x16x32_bf16 v[108:111], v[80:83], v[190:193], v[108:111]
	v_mfma_f32_16x16x32_bf16 v[96:99], v[72:75], v[198:201], v[96:99]
	v_mfma_f32_16x16x32_bf16 v[92:95], v[80:83], v[198:201], v[92:95]
	s_barrier
	s_add_i32 s84, 0, 0x14000
	v_add_u32_e32 v166, s84, v163
	s_add_i32 s0, s83, s54
	ds_read_b128 v[202:205], v166
	ds_read_b128 v[206:209], v166 offset:1024
	ds_read_b128 v[210:213], v166 offset:2048
	ds_read_b128 v[214:217], v166 offset:3072
	v_lshl_add_u64 v[166:167], s[26:27], 0, v[26:27]
	s_mov_b32 m0, s0
	v_lshl_add_u64 v[168:169], s[26:27], 0, v[148:149]
	s_setprio 0
	global_load_lds_dwordx4 v[166:167], off
	s_add_i32 m0, s0, 0x2000
	s_nop 0
	global_load_lds_dwordx4 v[168:169], off
	s_waitcnt vmcnt(10)
	s_setprio 1
	s_barrier
	s_waitcnt lgkmcnt(0)
	v_mfma_f32_16x16x32_bf16 v[136:139], v[202:205], v[158:161], v[136:139]
	v_mfma_f32_16x16x32_bf16 v[132:135], v[210:213], v[158:161], v[132:135]
	v_mfma_f32_16x16x32_bf16 v[120:123], v[202:205], v[178:181], v[120:123]
	v_mfma_f32_16x16x32_bf16 v[116:119], v[210:213], v[178:181], v[116:119]
	v_mfma_f32_16x16x32_bf16 v[104:107], v[202:205], v[186:189], v[104:107]
	v_mfma_f32_16x16x32_bf16 v[100:103], v[210:213], v[186:189], v[100:103]
	v_mfma_f32_16x16x32_bf16 v[88:91], v[202:205], v[194:197], v[88:91]
	v_mfma_f32_16x16x32_bf16 v[84:87], v[210:213], v[194:197], v[84:87]
	v_mfma_f32_16x16x32_bf16 v[136:139], v[206:209], v[174:177], v[136:139]
	v_mfma_f32_16x16x32_bf16 v[132:135], v[214:217], v[174:177], v[132:135]
	v_mfma_f32_16x16x32_bf16 v[120:123], v[206:209], v[182:185], v[120:123]
	v_mfma_f32_16x16x32_bf16 v[116:119], v[214:217], v[182:185], v[116:119]
	v_mfma_f32_16x16x32_bf16 v[104:107], v[206:209], v[190:193], v[104:107]
	v_mfma_f32_16x16x32_bf16 v[100:103], v[214:217], v[190:193], v[100:103]
	v_mfma_f32_16x16x32_bf16 v[88:91], v[206:209], v[198:201], v[88:91]
	v_mfma_f32_16x16x32_bf16 v[84:87], v[214:217], v[198:201], v[84:87]
	s_barrier
	s_mov_b32 m0, s23
	v_lshl_add_u64 v[218:219], s[28:29], 0, v[152:153]
	ds_read_b128 v[158:161], v165 offset:16384
	ds_read_b128 v[174:177], v165 offset:17408
	ds_read_b128 v[178:181], v165 offset:18432
	ds_read_b128 v[182:185], v165 offset:19456
	ds_read_b128 v[186:189], v165 offset:20480
	ds_read_b128 v[190:193], v165 offset:21504
	ds_read_b128 v[194:197], v165 offset:22528
	ds_read_b128 v[198:201], v165 offset:23552
	s_setprio 0
	global_load_lds_dwordx4 v[218:219], off
	v_lshl_add_u64 v[220:221], s[28:29], 0, v[150:151]
	s_mov_b32 m0, s57
	s_nop 0
	global_load_lds_dwordx4 v[220:221], off
	s_waitcnt vmcnt(10)
	s_setprio 1
	s_barrier
	s_waitcnt lgkmcnt(0)
	v_mfma_f32_16x16x32_bf16 v[64:67], v[68:71], v[158:161], v[64:67]
	v_mfma_f32_16x16x32_bf16 v[60:63], v[76:79], v[158:161], v[60:63]
	v_mfma_f32_16x16x32_bf16 v[48:51], v[68:71], v[178:181], v[48:51]
	v_mfma_f32_16x16x32_bf16 v[44:47], v[76:79], v[178:181], v[44:47]
	v_mfma_f32_16x16x32_bf16 v[32:35], v[68:71], v[186:189], v[32:35]
	v_mfma_f32_16x16x32_bf16 v[28:31], v[76:79], v[186:189], v[28:31]
	v_mfma_f32_16x16x32_bf16 v[14:17], v[68:71], v[194:197], v[14:17]
	v_mfma_f32_16x16x32_bf16 v[10:13], v[76:79], v[194:197], v[10:13]
	v_mfma_f32_16x16x32_bf16 v[64:67], v[72:75], v[174:177], v[64:67]
	v_mfma_f32_16x16x32_bf16 v[60:63], v[80:83], v[174:177], v[60:63]
	v_mfma_f32_16x16x32_bf16 v[48:51], v[72:75], v[182:185], v[48:51]
	v_mfma_f32_16x16x32_bf16 v[44:47], v[80:83], v[182:185], v[44:47]
	v_mfma_f32_16x16x32_bf16 v[32:35], v[72:75], v[190:193], v[32:35]
	v_mfma_f32_16x16x32_bf16 v[28:31], v[80:83], v[190:193], v[28:31]
	v_mfma_f32_16x16x32_bf16 v[14:17], v[72:75], v[198:201], v[14:17]
	v_mfma_f32_16x16x32_bf16 v[10:13], v[80:83], v[198:201], v[10:13]
	s_barrier
	s_add_u32 s0, s26, 0x40000
	s_addc_u32 s1, s27, 0
	s_add_i32 s83, s84, s54
	s_setprio 0
	s_mov_b32 m0, s83
	s_nop 0
	global_load_lds_dwordx4 v26, s[0:1]
	s_add_i32 m0, s83, 0x2000
	s_nop 0
	global_load_lds_dwordx4 v148, s[0:1]
	v_add_u32_e32 v80, 0x18000, v163
	ds_read_b128 v[68:71], v80
	ds_read_b128 v[72:75], v80 offset:1024
	ds_read_b128 v[76:79], v80 offset:2048
	ds_read_b128 v[80:83], v80 offset:3072
	s_waitcnt vmcnt(10)
	s_setprio 1
	s_barrier
	v_mfma_f32_16x16x32_bf16 v[56:59], v[202:205], v[158:161], v[56:59]
	v_mfma_f32_16x16x32_bf16 v[52:55], v[210:213], v[158:161], v[52:55]
	v_mfma_f32_16x16x32_bf16 v[40:43], v[202:205], v[178:181], v[40:43]
	v_mfma_f32_16x16x32_bf16 v[36:39], v[210:213], v[178:181], v[36:39]
	v_mfma_f32_16x16x32_bf16 v[22:25], v[202:205], v[186:189], v[22:25]
	v_mfma_f32_16x16x32_bf16 v[18:21], v[210:213], v[186:189], v[18:21]
	v_mfma_f32_16x16x32_bf16 v[6:9], v[202:205], v[194:197], v[6:9]
	v_mfma_f32_16x16x32_bf16 v[2:5], v[210:213], v[194:197], v[2:5]
	v_mfma_f32_16x16x32_bf16 v[56:59], v[206:209], v[174:177], v[56:59]
	v_mfma_f32_16x16x32_bf16 v[52:55], v[214:217], v[174:177], v[52:55]
	v_mfma_f32_16x16x32_bf16 v[40:43], v[206:209], v[182:185], v[40:43]
	v_mfma_f32_16x16x32_bf16 v[36:39], v[214:217], v[182:185], v[36:39]
	v_mfma_f32_16x16x32_bf16 v[22:25], v[206:209], v[190:193], v[22:25]
	v_mfma_f32_16x16x32_bf16 v[18:21], v[214:217], v[190:193], v[18:21]
	v_mfma_f32_16x16x32_bf16 v[6:9], v[206:209], v[198:201], v[6:9]
	v_mfma_f32_16x16x32_bf16 v[2:5], v[214:217], v[198:201], v[2:5]
	s_barrier
	s_add_i32 s83, 0, 0x18000
	s_add_u32 s0, s28, 0x40000
	s_addc_u32 s1, s29, 0
	s_mov_b32 m0, s58
	ds_read_b128 v[158:161], v165 offset:32768
	ds_read_b128 v[174:177], v165 offset:33792
	ds_read_b128 v[178:181], v165 offset:34816
	ds_read_b128 v[182:185], v165 offset:35840
	ds_read_b128 v[186:189], v165 offset:36864
	ds_read_b128 v[190:193], v165 offset:37888
	ds_read_b128 v[194:197], v165 offset:38912
	ds_read_b128 v[198:201], v165 offset:39936
	s_setprio 0
	global_load_lds_dwordx4 v152, s[0:1]
	s_mov_b32 m0, s59
	s_nop 0
	global_load_lds_dwordx4 v150, s[0:1]
	s_waitcnt vmcnt(10) lgkmcnt(8)
	s_setprio 1
	s_barrier
	s_waitcnt lgkmcnt(0)
	v_mfma_f32_16x16x32_bf16 v[144:147], v[68:71], v[158:161], v[144:147]
	v_mfma_f32_16x16x32_bf16 v[140:143], v[76:79], v[158:161], v[140:143]
	v_mfma_f32_16x16x32_bf16 v[128:131], v[68:71], v[178:181], v[128:131]
	v_mfma_f32_16x16x32_bf16 v[124:127], v[76:79], v[178:181], v[124:127]
	v_mfma_f32_16x16x32_bf16 v[112:115], v[68:71], v[186:189], v[112:115]
	v_mfma_f32_16x16x32_bf16 v[108:111], v[76:79], v[186:189], v[108:111]
	v_mfma_f32_16x16x32_bf16 v[96:99], v[68:71], v[194:197], v[96:99]
	v_mfma_f32_16x16x32_bf16 v[92:95], v[76:79], v[194:197], v[92:95]
	v_mfma_f32_16x16x32_bf16 v[144:147], v[72:75], v[174:177], v[144:147]
	v_mfma_f32_16x16x32_bf16 v[140:143], v[80:83], v[174:177], v[140:143]
	v_mfma_f32_16x16x32_bf16 v[128:131], v[72:75], v[182:185], v[128:131]
	v_mfma_f32_16x16x32_bf16 v[124:127], v[80:83], v[182:185], v[124:127]
	v_mfma_f32_16x16x32_bf16 v[112:115], v[72:75], v[190:193], v[112:115]
	v_mfma_f32_16x16x32_bf16 v[108:111], v[80:83], v[190:193], v[108:111]
	v_mfma_f32_16x16x32_bf16 v[96:99], v[72:75], v[198:201], v[96:99]
	v_mfma_f32_16x16x32_bf16 v[92:95], v[80:83], v[198:201], v[92:95]
	s_barrier
	s_add_i32 s28, 0, 0x1c000
	s_add_i32 s0, s83, s54
	v_add_u32_e32 v173, s28, v163
	v_lshl_add_u64 v[166:167], v[166:167], 0, s[12:13]
	s_mov_b32 m0, s0
	ds_read_b128 v[202:205], v173
	ds_read_b128 v[206:209], v173 offset:1024
	ds_read_b128 v[210:213], v173 offset:2048
	ds_read_b128 v[214:217], v173 offset:3072
	s_setprio 0
	global_load_lds_dwordx4 v[166:167], off
	v_lshl_add_u64 v[166:167], v[168:169], 0, s[12:13]
	s_add_i32 m0, s0, 0x2000
	s_nop 0
	global_load_lds_dwordx4 v[166:167], off
	s_waitcnt vmcnt(10)
	s_setprio 1
	s_barrier
	s_waitcnt lgkmcnt(0)
	v_mfma_f32_16x16x32_bf16 v[136:139], v[202:205], v[158:161], v[136:139]
	v_mfma_f32_16x16x32_bf16 v[132:135], v[210:213], v[158:161], v[132:135]
	v_mfma_f32_16x16x32_bf16 v[120:123], v[202:205], v[178:181], v[120:123]
	v_mfma_f32_16x16x32_bf16 v[116:119], v[210:213], v[178:181], v[116:119]
	v_mfma_f32_16x16x32_bf16 v[104:107], v[202:205], v[186:189], v[104:107]
	v_mfma_f32_16x16x32_bf16 v[100:103], v[210:213], v[186:189], v[100:103]
	v_mfma_f32_16x16x32_bf16 v[88:91], v[202:205], v[194:197], v[88:91]
	v_mfma_f32_16x16x32_bf16 v[84:87], v[210:213], v[194:197], v[84:87]
	v_mfma_f32_16x16x32_bf16 v[136:139], v[206:209], v[174:177], v[136:139]
	v_mfma_f32_16x16x32_bf16 v[132:135], v[214:217], v[174:177], v[132:135]
	v_mfma_f32_16x16x32_bf16 v[120:123], v[206:209], v[182:185], v[120:123]
	v_mfma_f32_16x16x32_bf16 v[116:119], v[214:217], v[182:185], v[116:119]
	v_mfma_f32_16x16x32_bf16 v[104:107], v[206:209], v[190:193], v[104:107]
	v_mfma_f32_16x16x32_bf16 v[100:103], v[214:217], v[190:193], v[100:103]
	v_mfma_f32_16x16x32_bf16 v[88:91], v[206:209], v[198:201], v[88:91]
	v_mfma_f32_16x16x32_bf16 v[84:87], v[214:217], v[198:201], v[84:87]
	s_barrier
	s_mov_b32 m0, s34
	v_lshl_add_u64 v[166:167], v[218:219], 0, s[12:13]
	ds_read_b128 v[158:161], v165 offset:49152
	ds_read_b128 v[174:177], v165 offset:50176
	ds_read_b128 v[178:181], v165 offset:51200
	ds_read_b128 v[182:185], v165 offset:52224
	ds_read_b128 v[186:189], v165 offset:53248
	ds_read_b128 v[190:193], v165 offset:54272
	ds_read_b128 v[194:197], v165 offset:55296
	ds_read_b128 v[198:201], v165 offset:56320
	s_setprio 0
	global_load_lds_dwordx4 v[166:167], off
	v_lshl_add_u64 v[166:167], v[220:221], 0, s[12:13]
	s_mov_b32 m0, s35
	s_nop 0
	global_load_lds_dwordx4 v[166:167], off
	s_waitcnt vmcnt(10)
	s_setprio 1
	s_barrier
	s_waitcnt lgkmcnt(0)
	v_mfma_f32_16x16x32_bf16 v[64:67], v[68:71], v[158:161], v[64:67]
	v_mfma_f32_16x16x32_bf16 v[60:63], v[76:79], v[158:161], v[60:63]
	v_mfma_f32_16x16x32_bf16 v[48:51], v[68:71], v[178:181], v[48:51]
	v_mfma_f32_16x16x32_bf16 v[44:47], v[76:79], v[178:181], v[44:47]
	v_mfma_f32_16x16x32_bf16 v[32:35], v[68:71], v[186:189], v[32:35]
	v_mfma_f32_16x16x32_bf16 v[28:31], v[76:79], v[186:189], v[28:31]
	v_mfma_f32_16x16x32_bf16 v[14:17], v[68:71], v[194:197], v[14:17]
	v_mfma_f32_16x16x32_bf16 v[10:13], v[76:79], v[194:197], v[10:13]
	v_mfma_f32_16x16x32_bf16 v[64:67], v[72:75], v[174:177], v[64:67]
	v_mfma_f32_16x16x32_bf16 v[60:63], v[80:83], v[174:177], v[60:63]
	v_mfma_f32_16x16x32_bf16 v[48:51], v[72:75], v[182:185], v[48:51]
	v_mfma_f32_16x16x32_bf16 v[44:47], v[80:83], v[182:185], v[44:47]
	v_mfma_f32_16x16x32_bf16 v[32:35], v[72:75], v[190:193], v[32:35]
	v_mfma_f32_16x16x32_bf16 v[28:31], v[80:83], v[190:193], v[28:31]
	v_mfma_f32_16x16x32_bf16 v[14:17], v[72:75], v[198:201], v[14:17]
	v_mfma_f32_16x16x32_bf16 v[10:13], v[80:83], v[198:201], v[10:13]
	s_barrier
	s_add_u32 s0, s26, 0x40080
	s_addc_u32 s1, s27, 0
	s_add_i32 s26, s28, s54
	s_setprio 0
	s_mov_b32 m0, s26
	s_nop 0
	global_load_lds_dwordx4 v26, s[0:1]
	s_add_i32 m0, s26, 0x2000
	s_nop 0
	global_load_lds_dwordx4 v148, s[0:1]
	v_add_u32_e32 v80, 0x10000, v163
	ds_read_b128 v[68:71], v80
	ds_read_b128 v[72:75], v80 offset:1024
	ds_read_b128 v[76:79], v80 offset:2048
	ds_read_b128 v[80:83], v80 offset:3072
	s_add_i32 s82, s82, 2
	s_add_u32 s24, s24, 0x100
	s_addc_u32 s25, s25, 0
	s_add_u32 s73, s73, 0x100
	s_addc_u32 s81, s81, 0
	s_cmp_gt_u32 s82, 13
	s_cbranch_scc1 .Lth__1048
	s_add_u32 s0, s24, 0xfffc0080
	s_addc_u32 s1, s25, -1
	s_add_i32 s83, 0, 0x10000
	s_cmp_eq_u32 s82, 12
	s_cselect_b32 s29, s43, s1
	s_cselect_b32 s28, s69, s0
	s_cselect_b32 s27, s45, s81
	s_cselect_b32 s26, s72, s73
	s_cmp_gt_u32 s82, 13

.LBB0_1122:
	s_add_i32 m0, s36, 0xc000
	ds_read_b128 v[162:165], v188
	ds_read_b128 v[172:175], v188 offset:1024
	ds_read_b128 v[176:179], v188 offset:2048
	ds_read_b128 v[180:183], v188 offset:3072
	ds_read_b128 v[190:193], v188 offset:4096
	ds_read_b128 v[194:197], v188 offset:5120
	ds_read_b128 v[198:201], v188 offset:6144
	ds_read_b128 v[202:205], v188 offset:7168
	global_load_lds_dwordx4 v150, s[24:25]
	v_lshl_add_u64 v[166:167], s[24:25], 0, v[152:153]
	s_add_i32 m0, s36, 0xe000
	s_nop 0
	global_load_lds_dwordx4 v[166:167], off
	s_waitcnt vmcnt(10) lgkmcnt(8)
	s_setprio 1
	s_barrier
	s_waitcnt lgkmcnt(0)
	v_mfma_f32_16x16x32_bf16 v[128:131], v[132:135], v[162:165], v[128:131]
	v_mfma_f32_16x16x32_bf16 v[124:127], v[154:157], v[162:165], v[124:127]
	v_mfma_f32_16x16x32_bf16 v[120:123], v[132:135], v[176:179], v[120:123]
	v_mfma_f32_16x16x32_bf16 v[116:119], v[154:157], v[176:179], v[116:119]
	v_mfma_f32_16x16x32_bf16 v[112:115], v[132:135], v[190:193], v[112:115]
	v_mfma_f32_16x16x32_bf16 v[108:111], v[154:157], v[190:193], v[108:111]
	v_mfma_f32_16x16x32_bf16 v[104:107], v[132:135], v[198:201], v[104:107]
	v_mfma_f32_16x16x32_bf16 v[100:103], v[154:157], v[198:201], v[100:103]
	v_mfma_f32_16x16x32_bf16 v[128:131], v[136:139], v[172:175], v[128:131]
	v_mfma_f32_16x16x32_bf16 v[124:127], v[158:161], v[172:175], v[124:127]
	v_mfma_f32_16x16x32_bf16 v[120:123], v[136:139], v[180:183], v[120:123]
	v_mfma_f32_16x16x32_bf16 v[116:119], v[158:161], v[180:183], v[116:119]
	v_mfma_f32_16x16x32_bf16 v[112:115], v[136:139], v[194:197], v[112:115]
	v_mfma_f32_16x16x32_bf16 v[108:111], v[158:161], v[194:197], v[108:111]
	v_mfma_f32_16x16x32_bf16 v[104:107], v[136:139], v[202:205], v[104:107]
	v_mfma_f32_16x16x32_bf16 v[100:103], v[158:161], v[202:205], v[100:103]
	s_barrier
	s_add_i32 s24, 0, 0x14000
	v_add_u32_e32 v166, s24, v186
	s_add_i32 s0, s0, s17
	ds_read_b128 v[206:209], v166
	ds_read_b128 v[210:213], v166 offset:1024
	ds_read_b128 v[214:217], v166 offset:2048
	ds_read_b128 v[218:221], v166 offset:3072
	v_lshl_add_u64 v[166:167], s[28:29], 0, v[26:27]
	s_mov_b32 m0, s0
	v_lshl_add_u64 v[168:169], s[28:29], 0, v[144:145]
	s_setprio 0
	global_load_lds_dwordx4 v[166:167], off
	s_add_i32 m0, s0, 0x2000
	s_nop 0
	global_load_lds_dwordx4 v[168:169], off
	s_waitcnt vmcnt(10)
	s_setprio 1
	s_barrier
	s_waitcnt lgkmcnt(0)
	v_mfma_f32_16x16x32_bf16 v[68:71], v[206:209], v[162:165], v[68:71]
	v_mfma_f32_16x16x32_bf16 v[60:63], v[214:217], v[162:165], v[60:63]
	v_mfma_f32_16x16x32_bf16 v[56:59], v[206:209], v[176:179], v[56:59]
	v_mfma_f32_16x16x32_bf16 v[52:55], v[214:217], v[176:179], v[52:55]
	v_mfma_f32_16x16x32_bf16 v[48:51], v[206:209], v[190:193], v[48:51]
	v_mfma_f32_16x16x32_bf16 v[44:47], v[214:217], v[190:193], v[44:47]
	v_mfma_f32_16x16x32_bf16 v[40:43], v[206:209], v[198:201], v[40:43]
	v_mfma_f32_16x16x32_bf16 v[36:39], v[214:217], v[198:201], v[36:39]
	v_mfma_f32_16x16x32_bf16 v[68:71], v[210:213], v[172:175], v[68:71]
	v_mfma_f32_16x16x32_bf16 v[60:63], v[218:221], v[172:175], v[60:63]
	v_mfma_f32_16x16x32_bf16 v[56:59], v[210:213], v[180:183], v[56:59]
	v_mfma_f32_16x16x32_bf16 v[52:55], v[218:221], v[180:183], v[52:55]
	v_mfma_f32_16x16x32_bf16 v[48:51], v[210:213], v[194:197], v[48:51]
	v_mfma_f32_16x16x32_bf16 v[44:47], v[218:221], v[194:197], v[44:47]
	v_mfma_f32_16x16x32_bf16 v[40:43], v[210:213], v[202:205], v[40:43]
	v_mfma_f32_16x16x32_bf16 v[36:39], v[218:221], v[202:205], v[36:39]
	s_barrier
	s_mov_b32 m0, s36
	v_lshl_add_u64 v[184:185], s[30:31], 0, v[140:141]
	ds_read_b128 v[162:165], v188 offset:16384
	ds_read_b128 v[172:175], v188 offset:17408
	ds_read_b128 v[176:179], v188 offset:18432
	ds_read_b128 v[180:183], v188 offset:19456
	ds_read_b128 v[190:193], v188 offset:20480
	ds_read_b128 v[194:197], v188 offset:21504
	ds_read_b128 v[198:201], v188 offset:22528
	ds_read_b128 v[202:205], v188 offset:23552
	s_setprio 0
	global_load_lds_dwordx4 v[184:185], off
	v_lshl_add_u64 v[222:223], s[30:31], 0, v[142:143]
	s_mov_b32 m0, s37
	s_nop 0
	global_load_lds_dwordx4 v[222:223], off
	s_waitcnt vmcnt(10)
	s_setprio 1
	s_barrier
	s_waitcnt lgkmcnt(0)
	v_mfma_f32_16x16x32_bf16 v[96:99], v[132:135], v[162:165], v[96:99]
	v_mfma_f32_16x16x32_bf16 v[92:95], v[154:157], v[162:165], v[92:95]
	v_mfma_f32_16x16x32_bf16 v[88:91], v[132:135], v[176:179], v[88:91]
	v_mfma_f32_16x16x32_bf16 v[84:87], v[154:157], v[176:179], v[84:87]
	v_mfma_f32_16x16x32_bf16 v[80:83], v[132:135], v[190:193], v[80:83]
	v_mfma_f32_16x16x32_bf16 v[76:79], v[154:157], v[190:193], v[76:79]
	v_mfma_f32_16x16x32_bf16 v[72:75], v[132:135], v[198:201], v[72:75]
	v_mfma_f32_16x16x32_bf16 v[64:67], v[154:157], v[198:201], v[64:67]
	v_mfma_f32_16x16x32_bf16 v[96:99], v[136:139], v[172:175], v[96:99]
	v_mfma_f32_16x16x32_bf16 v[92:95], v[158:161], v[172:175], v[92:95]
	v_mfma_f32_16x16x32_bf16 v[88:91], v[136:139], v[180:183], v[88:91]
	v_mfma_f32_16x16x32_bf16 v[84:87], v[158:161], v[180:183], v[84:87]
	v_mfma_f32_16x16x32_bf16 v[80:83], v[136:139], v[194:197], v[80:83]
	v_mfma_f32_16x16x32_bf16 v[76:79], v[158:161], v[194:197], v[76:79]
	v_mfma_f32_16x16x32_bf16 v[72:75], v[136:139], v[202:205], v[72:75]
	v_mfma_f32_16x16x32_bf16 v[64:67], v[158:161], v[202:205], v[64:67]
	s_barrier
	s_add_u32 s0, s28, 0xb0000
	s_addc_u32 s1, s29, 0
	s_add_i32 s24, s24, s17
	s_setprio 0
	s_mov_b32 m0, s24
	s_nop 0
	global_load_lds_dwordx4 v26, s[0:1]
	s_add_i32 m0, s24, 0x2000
	s_nop 0
	global_load_lds_dwordx4 v144, s[0:1]
	v_add_u32_e32 v158, 0x18000, v186
	ds_read_b128 v[132:135], v158
	ds_read_b128 v[136:139], v158 offset:1024
	ds_read_b128 v[154:157], v158 offset:2048
	ds_read_b128 v[158:161], v158 offset:3072
	s_waitcnt vmcnt(10)
	s_setprio 1
	s_barrier
	v_mfma_f32_16x16x32_bf16 v[32:35], v[206:209], v[162:165], v[32:35]
	v_mfma_f32_16x16x32_bf16 v[28:31], v[214:217], v[162:165], v[28:31]
	v_mfma_f32_16x16x32_bf16 v[22:25], v[206:209], v[176:179], v[22:25]
	v_mfma_f32_16x16x32_bf16 v[18:21], v[214:217], v[176:179], v[18:21]
	v_mfma_f32_16x16x32_bf16 v[14:17], v[206:209], v[190:193], v[14:17]
	v_mfma_f32_16x16x32_bf16 v[10:13], v[214:217], v[190:193], v[10:13]
	v_mfma_f32_16x16x32_bf16 v[6:9], v[206:209], v[198:201], v[6:9]
	v_mfma_f32_16x16x32_bf16 v[2:5], v[214:217], v[198:201], v[2:5]
	v_mfma_f32_16x16x32_bf16 v[32:35], v[210:213], v[172:175], v[32:35]
	v_mfma_f32_16x16x32_bf16 v[28:31], v[218:221], v[172:175], v[28:31]
	v_mfma_f32_16x16x32_bf16 v[22:25], v[210:213], v[180:183], v[22:25]
	v_mfma_f32_16x16x32_bf16 v[18:21], v[218:221], v[180:183], v[18:21]
	v_mfma_f32_16x16x32_bf16 v[14:17], v[210:213], v[194:197], v[14:17]
	v_mfma_f32_16x16x32_bf16 v[10:13], v[218:221], v[194:197], v[10:13]
	v_mfma_f32_16x16x32_bf16 v[6:9], v[210:213], v[202:205], v[6:9]
	v_mfma_f32_16x16x32_bf16 v[2:5], v[218:221], v[202:205], v[2:5]
	s_barrier
	s_add_i32 s24, 0, 0x18000
	s_add_u32 s0, s30, 0xb0000
	s_addc_u32 s1, s31, 0
	s_mov_b32 m0, s52
	ds_read_b128 v[162:165], v188 offset:32768
	ds_read_b128 v[172:175], v188 offset:33792
	ds_read_b128 v[176:179], v188 offset:34816
	ds_read_b128 v[180:183], v188 offset:35840
	ds_read_b128 v[190:193], v188 offset:36864
	ds_read_b128 v[194:197], v188 offset:37888
	ds_read_b128 v[198:201], v188 offset:38912
	ds_read_b128 v[202:205], v188 offset:39936
	s_setprio 0
	global_load_lds_dwordx4 v140, s[0:1]
	s_mov_b32 m0, s54
	s_nop 0
	global_load_lds_dwordx4 v142, s[0:1]
	s_waitcnt vmcnt(10) lgkmcnt(8)
	s_setprio 1
	s_barrier
	s_waitcnt lgkmcnt(0)
	v_mfma_f32_16x16x32_bf16 v[128:131], v[132:135], v[162:165], v[128:131]
	v_mfma_f32_16x16x32_bf16 v[124:127], v[154:157], v[162:165], v[124:127]
	v_mfma_f32_16x16x32_bf16 v[120:123], v[132:135], v[176:179], v[120:123]
	v_mfma_f32_16x16x32_bf16 v[116:119], v[154:157], v[176:179], v[116:119]
	v_mfma_f32_16x16x32_bf16 v[112:115], v[132:135], v[190:193], v[112:115]
	v_mfma_f32_16x16x32_bf16 v[108:111], v[154:157], v[190:193], v[108:111]
	v_mfma_f32_16x16x32_bf16 v[104:107], v[132:135], v[198:201], v[104:107]
	v_mfma_f32_16x16x32_bf16 v[100:103], v[154:157], v[198:201], v[100:103]
	v_mfma_f32_16x16x32_bf16 v[128:131], v[136:139], v[172:175], v[128:131]
	v_mfma_f32_16x16x32_bf16 v[124:127], v[158:161], v[172:175], v[124:127]
	v_mfma_f32_16x16x32_bf16 v[120:123], v[136:139], v[180:183], v[120:123]
	v_mfma_f32_16x16x32_bf16 v[116:119], v[158:161], v[180:183], v[116:119]
	v_mfma_f32_16x16x32_bf16 v[112:115], v[136:139], v[194:197], v[112:115]
	v_mfma_f32_16x16x32_bf16 v[108:111], v[158:161], v[194:197], v[108:111]
	v_mfma_f32_16x16x32_bf16 v[104:107], v[136:139], v[202:205], v[104:107]
	v_mfma_f32_16x16x32_bf16 v[100:103], v[158:161], v[202:205], v[100:103]
	s_barrier
	s_add_i32 s25, 0, 0x1c000
	s_add_i32 s0, s24, s17
	v_add_u32_e32 v189, s25, v186
	v_lshl_add_u64 v[166:167], v[166:167], 0, s[12:13]
	s_mov_b32 m0, s0
	ds_read_b128 v[206:209], v189
	ds_read_b128 v[210:213], v189 offset:1024
	ds_read_b128 v[214:217], v189 offset:2048
	ds_read_b128 v[218:221], v189 offset:3072
	s_setprio 0
	global_load_lds_dwordx4 v[166:167], off
	v_lshl_add_u64 v[166:167], v[168:169], 0, s[12:13]
	s_add_i32 m0, s0, 0x2000
	s_nop 0
	global_load_lds_dwordx4 v[166:167], off
	s_waitcnt vmcnt(10)
	s_setprio 1
	s_barrier
	s_waitcnt lgkmcnt(0)
	v_mfma_f32_16x16x32_bf16 v[68:71], v[206:209], v[162:165], v[68:71]
	v_mfma_f32_16x16x32_bf16 v[60:63], v[214:217], v[162:165], v[60:63]
	v_mfma_f32_16x16x32_bf16 v[56:59], v[206:209], v[176:179], v[56:59]
	v_mfma_f32_16x16x32_bf16 v[52:55], v[214:217], v[176:179], v[52:55]
	v_mfma_f32_16x16x32_bf16 v[48:51], v[206:209], v[190:193], v[48:51]
	v_mfma_f32_16x16x32_bf16 v[44:47], v[214:217], v[190:193], v[44:47]
	v_mfma_f32_16x16x32_bf16 v[40:43], v[206:209], v[198:201], v[40:43]
	v_mfma_f32_16x16x32_bf16 v[36:39], v[214:217], v[198:201], v[36:39]
	v_mfma_f32_16x16x32_bf16 v[68:71], v[210:213], v[172:175], v[68:71]
	v_mfma_f32_16x16x32_bf16 v[60:63], v[218:221], v[172:175], v[60:63]
	v_mfma_f32_16x16x32_bf16 v[56:59], v[210:213], v[180:183], v[56:59]
	v_mfma_f32_16x16x32_bf16 v[52:55], v[218:221], v[180:183], v[52:55]
	v_mfma_f32_16x16x32_bf16 v[48:51], v[210:213], v[194:197], v[48:51]
	v_mfma_f32_16x16x32_bf16 v[44:47], v[218:221], v[194:197], v[44:47]
	v_mfma_f32_16x16x32_bf16 v[40:43], v[210:213], v[202:205], v[40:43]
	v_mfma_f32_16x16x32_bf16 v[36:39], v[218:221], v[202:205], v[36:39]
	s_barrier
	s_mov_b32 m0, s55
	v_lshl_add_u64 v[166:167], v[184:185], 0, s[12:13]
	ds_read_b128 v[162:165], v188 offset:49152
	ds_read_b128 v[172:175], v188 offset:50176
	ds_read_b128 v[176:179], v188 offset:51200
	ds_read_b128 v[180:183], v188 offset:52224
	ds_read_b128 v[190:193], v188 offset:53248
	ds_read_b128 v[194:197], v188 offset:54272
	ds_read_b128 v[198:201], v188 offset:55296
	ds_read_b128 v[202:205], v188 offset:56320
	s_setprio 0
	global_load_lds_dwordx4 v[166:167], off
	v_lshl_add_u64 v[166:167], v[222:223], 0, s[12:13]
	s_mov_b32 m0, s56
	s_nop 0
	global_load_lds_dwordx4 v[166:167], off
	s_waitcnt vmcnt(10)
	s_setprio 1
	s_barrier
	s_waitcnt lgkmcnt(0)
	v_mfma_f32_16x16x32_bf16 v[96:99], v[132:135], v[162:165], v[96:99]
	v_mfma_f32_16x16x32_bf16 v[92:95], v[154:157], v[162:165], v[92:95]
	v_mfma_f32_16x16x32_bf16 v[88:91], v[132:135], v[176:179], v[88:91]
	v_mfma_f32_16x16x32_bf16 v[84:87], v[154:157], v[176:179], v[84:87]
	v_mfma_f32_16x16x32_bf16 v[80:83], v[132:135], v[190:193], v[80:83]
	v_mfma_f32_16x16x32_bf16 v[76:79], v[154:157], v[190:193], v[76:79]
	v_mfma_f32_16x16x32_bf16 v[72:75], v[132:135], v[198:201], v[72:75]
	v_mfma_f32_16x16x32_bf16 v[64:67], v[154:157], v[198:201], v[64:67]
	v_mfma_f32_16x16x32_bf16 v[96:99], v[136:139], v[172:175], v[96:99]
	v_mfma_f32_16x16x32_bf16 v[92:95], v[158:161], v[172:175], v[92:95]
	v_mfma_f32_16x16x32_bf16 v[88:91], v[136:139], v[180:183], v[88:91]
	v_mfma_f32_16x16x32_bf16 v[84:87], v[158:161], v[180:183], v[84:87]
	v_mfma_f32_16x16x32_bf16 v[80:83], v[136:139], v[194:197], v[80:83]
	v_mfma_f32_16x16x32_bf16 v[76:79], v[158:161], v[194:197], v[76:79]
	v_mfma_f32_16x16x32_bf16 v[72:75], v[136:139], v[202:205], v[72:75]
	v_mfma_f32_16x16x32_bf16 v[64:67], v[158:161], v[202:205], v[64:67]
	s_barrier
	s_add_u32 s0, s28, 0xb0080
	s_addc_u32 s1, s29, 0
	s_add_i32 s24, s25, s17
	s_setprio 0
	s_mov_b32 m0, s24
	s_nop 0
	global_load_lds_dwordx4 v26, s[0:1]
	s_add_i32 m0, s24, 0x2000
	s_nop 0
	global_load_lds_dwordx4 v144, s[0:1]
	v_add_u32_e32 v158, 0x10000, v186
	ds_read_b128 v[132:135], v158
	ds_read_b128 v[136:139], v158 offset:1024
	ds_read_b128 v[154:157], v158 offset:2048
	ds_read_b128 v[158:161], v158 offset:3072
	s_add_i32 s72, s72, 2
	s_add_u32 s68, s68, 0x100
	s_addc_u32 s69, s69, 0
	s_mov_b64 s[24:25], s[26:27]
	s_cmp_gt_u32 s72, 41
	s_cbranch_scc1 .Lth__1122
	s_add_u32 s26, s24, 0x100
	s_addc_u32 s27, s25, 0
	s_add_i32 s0, 0, 0x10000
	s_cmp_eq_u32 s72, 40
	s_cselect_b32 s31, s43, s27
	s_cselect_b32 s30, s42, s26
	s_cselect_b32 s29, s45, s69
	s_cselect_b32 s28, s44, s68
	s_cmp_gt_u32 s72, 41

.LBB0_1156:
	s_add_i32 m0, s52, 0xc000
	ds_read_b128 v[172:175], v224
	ds_read_b128 v[176:179], v224 offset:1024
	ds_read_b128 v[180:183], v224 offset:2048
	ds_read_b128 v[184:187], v224 offset:3072
	ds_read_b128 v[188:191], v224 offset:4096
	ds_read_b128 v[192:195], v224 offset:5120
	ds_read_b128 v[196:199], v224 offset:6144
	ds_read_b128 v[200:203], v224 offset:7168
	global_load_lds_dwordx4 v152, s[26:27]
	v_lshl_add_u64 v[164:165], s[26:27], 0, v[154:155]
	s_add_i32 m0, s52, 0xe000
	s_nop 0
	global_load_lds_dwordx4 v[164:165], off
	s_waitcnt vmcnt(10) lgkmcnt(8)
	s_setprio 1
	s_barrier
	s_waitcnt lgkmcnt(0)
	v_mfma_f32_16x16x32_bf16 v[128:131], v[132:135], v[172:175], v[128:131]
	v_mfma_f32_16x16x32_bf16 v[124:127], v[156:159], v[172:175], v[124:127]
	v_mfma_f32_16x16x32_bf16 v[120:123], v[132:135], v[180:183], v[120:123]
	v_mfma_f32_16x16x32_bf16 v[116:119], v[156:159], v[180:183], v[116:119]
	v_mfma_f32_16x16x32_bf16 v[112:115], v[132:135], v[188:191], v[112:115]
	v_mfma_f32_16x16x32_bf16 v[108:111], v[156:159], v[188:191], v[108:111]
	v_mfma_f32_16x16x32_bf16 v[104:107], v[132:135], v[196:199], v[104:107]
	v_mfma_f32_16x16x32_bf16 v[100:103], v[156:159], v[196:199], v[100:103]
	v_mfma_f32_16x16x32_bf16 v[128:131], v[136:139], v[176:179], v[128:131]
	v_mfma_f32_16x16x32_bf16 v[124:127], v[160:163], v[176:179], v[124:127]
	v_mfma_f32_16x16x32_bf16 v[120:123], v[136:139], v[184:187], v[120:123]
	v_mfma_f32_16x16x32_bf16 v[116:119], v[160:163], v[184:187], v[116:119]
	v_mfma_f32_16x16x32_bf16 v[112:115], v[136:139], v[192:195], v[112:115]
	v_mfma_f32_16x16x32_bf16 v[108:111], v[160:163], v[192:195], v[108:111]
	v_mfma_f32_16x16x32_bf16 v[104:107], v[136:139], v[200:203], v[104:107]
	v_mfma_f32_16x16x32_bf16 v[100:103], v[160:163], v[200:203], v[100:103]
	s_barrier
	s_add_i32 s26, 0, 0x14000
	v_add_u32_e32 v164, s26, v222
	s_add_i32 s0, s0, s17
	ds_read_b128 v[204:207], v164
	ds_read_b128 v[208:211], v164 offset:1024
	ds_read_b128 v[212:215], v164 offset:2048
	ds_read_b128 v[216:219], v164 offset:3072
	v_lshl_add_u64 v[164:165], s[30:31], 0, v[26:27]
	s_mov_b32 m0, s0
	v_lshl_add_u64 v[166:167], s[30:31], 0, v[144:145]
	s_setprio 0
	global_load_lds_dwordx4 v[164:165], off
	s_add_i32 m0, s0, 0x2000
	s_nop 0
	global_load_lds_dwordx4 v[166:167], off
	s_waitcnt vmcnt(10)
	s_setprio 1
	s_barrier
	s_waitcnt lgkmcnt(0)
	v_mfma_f32_16x16x32_bf16 v[64:67], v[204:207], v[172:175], v[64:67]
	v_mfma_f32_16x16x32_bf16 v[60:63], v[212:215], v[172:175], v[60:63]
	v_mfma_f32_16x16x32_bf16 v[56:59], v[204:207], v[180:183], v[56:59]
	v_mfma_f32_16x16x32_bf16 v[52:55], v[212:215], v[180:183], v[52:55]
	v_mfma_f32_16x16x32_bf16 v[48:51], v[204:207], v[188:191], v[48:51]
	v_mfma_f32_16x16x32_bf16 v[44:47], v[212:215], v[188:191], v[44:47]
	v_mfma_f32_16x16x32_bf16 v[40:43], v[204:207], v[196:199], v[40:43]
	v_mfma_f32_16x16x32_bf16 v[36:39], v[212:215], v[196:199], v[36:39]
	v_mfma_f32_16x16x32_bf16 v[64:67], v[208:211], v[176:179], v[64:67]
	v_mfma_f32_16x16x32_bf16 v[60:63], v[216:219], v[176:179], v[60:63]
	v_mfma_f32_16x16x32_bf16 v[56:59], v[208:211], v[184:187], v[56:59]
	v_mfma_f32_16x16x32_bf16 v[52:55], v[216:219], v[184:187], v[52:55]
	v_mfma_f32_16x16x32_bf16 v[48:51], v[208:211], v[192:195], v[48:51]
	v_mfma_f32_16x16x32_bf16 v[44:47], v[216:219], v[192:195], v[44:47]
	v_mfma_f32_16x16x32_bf16 v[40:43], v[208:211], v[200:203], v[40:43]
	v_mfma_f32_16x16x32_bf16 v[36:39], v[216:219], v[200:203], v[36:39]
	s_barrier
	s_mov_b32 m0, s52
	v_lshl_add_u64 v[168:169], s[34:35], 0, v[140:141]
	ds_read_b128 v[172:175], v224 offset:16384
	ds_read_b128 v[176:179], v224 offset:17408
	ds_read_b128 v[180:183], v224 offset:18432
	ds_read_b128 v[184:187], v224 offset:19456
	ds_read_b128 v[188:191], v224 offset:20480
	ds_read_b128 v[192:195], v224 offset:21504
	ds_read_b128 v[196:199], v224 offset:22528
	ds_read_b128 v[200:203], v224 offset:23552
	s_setprio 0
	global_load_lds_dwordx4 v[168:169], off
	v_lshl_add_u64 v[220:221], s[34:35], 0, v[142:143]
	s_mov_b32 m0, s54
	s_nop 0
	global_load_lds_dwordx4 v[220:221], off
	s_waitcnt vmcnt(10)
	s_setprio 1
	s_barrier
	s_waitcnt lgkmcnt(0)
	v_mfma_f32_16x16x32_bf16 v[96:99], v[132:135], v[172:175], v[96:99]
	v_mfma_f32_16x16x32_bf16 v[92:95], v[156:159], v[172:175], v[92:95]
	v_mfma_f32_16x16x32_bf16 v[88:91], v[132:135], v[180:183], v[88:91]
	v_mfma_f32_16x16x32_bf16 v[84:87], v[156:159], v[180:183], v[84:87]
	v_mfma_f32_16x16x32_bf16 v[80:83], v[132:135], v[188:191], v[80:83]
	v_mfma_f32_16x16x32_bf16 v[76:79], v[156:159], v[188:191], v[76:79]
	v_mfma_f32_16x16x32_bf16 v[72:75], v[132:135], v[196:199], v[72:75]
	v_mfma_f32_16x16x32_bf16 v[68:71], v[156:159], v[196:199], v[68:71]
	v_mfma_f32_16x16x32_bf16 v[96:99], v[136:139], v[176:179], v[96:99]
	v_mfma_f32_16x16x32_bf16 v[92:95], v[160:163], v[176:179], v[92:95]
	v_mfma_f32_16x16x32_bf16 v[88:91], v[136:139], v[184:187], v[88:91]
	v_mfma_f32_16x16x32_bf16 v[84:87], v[160:163], v[184:187], v[84:87]
	v_mfma_f32_16x16x32_bf16 v[80:83], v[136:139], v[192:195], v[80:83]
	v_mfma_f32_16x16x32_bf16 v[76:79], v[160:163], v[192:195], v[76:79]
	v_mfma_f32_16x16x32_bf16 v[72:75], v[136:139], v[200:203], v[72:75]
	v_mfma_f32_16x16x32_bf16 v[68:71], v[160:163], v[200:203], v[68:71]
	s_barrier
	s_add_u32 s0, s30, 0xb0000
	s_addc_u32 s1, s31, 0
	s_add_i32 s26, s26, s17
	s_setprio 0
	s_mov_b32 m0, s26
	s_nop 0
	global_load_lds_dwordx4 v26, s[0:1]
	s_add_i32 m0, s26, 0x2000
	s_nop 0
	global_load_lds_dwordx4 v144, s[0:1]
	v_add_u32_e32 v160, 0x18000, v222
	ds_read_b128 v[132:135], v160
	ds_read_b128 v[136:139], v160 offset:1024
	ds_read_b128 v[156:159], v160 offset:2048
	ds_read_b128 v[160:163], v160 offset:3072
	s_waitcnt vmcnt(10)
	s_setprio 1
	s_barrier
	v_mfma_f32_16x16x32_bf16 v[32:35], v[204:207], v[172:175], v[32:35]
	v_mfma_f32_16x16x32_bf16 v[28:31], v[212:215], v[172:175], v[28:31]
	v_mfma_f32_16x16x32_bf16 v[22:25], v[204:207], v[180:183], v[22:25]
	v_mfma_f32_16x16x32_bf16 v[18:21], v[212:215], v[180:183], v[18:21]
	v_mfma_f32_16x16x32_bf16 v[14:17], v[204:207], v[188:191], v[14:17]
	v_mfma_f32_16x16x32_bf16 v[10:13], v[212:215], v[188:191], v[10:13]
	v_mfma_f32_16x16x32_bf16 v[6:9], v[204:207], v[196:199], v[6:9]
	v_mfma_f32_16x16x32_bf16 v[2:5], v[212:215], v[196:199], v[2:5]
	v_mfma_f32_16x16x32_bf16 v[32:35], v[208:211], v[176:179], v[32:35]
	v_mfma_f32_16x16x32_bf16 v[28:31], v[216:219], v[176:179], v[28:31]
	v_mfma_f32_16x16x32_bf16 v[22:25], v[208:211], v[184:187], v[22:25]
	v_mfma_f32_16x16x32_bf16 v[18:21], v[216:219], v[184:187], v[18:21]
	v_mfma_f32_16x16x32_bf16 v[14:17], v[208:211], v[192:195], v[14:17]
	v_mfma_f32_16x16x32_bf16 v[10:13], v[216:219], v[192:195], v[10:13]
	v_mfma_f32_16x16x32_bf16 v[6:9], v[208:211], v[200:203], v[6:9]
	v_mfma_f32_16x16x32_bf16 v[2:5], v[216:219], v[200:203], v[2:5]
	s_barrier
	s_add_i32 s26, 0, 0x18000
	s_add_u32 s0, s34, 0xb0000
	s_addc_u32 s1, s35, 0
	s_mov_b32 m0, s55
	ds_read_b128 v[172:175], v224 offset:32768
	ds_read_b128 v[176:179], v224 offset:33792
	ds_read_b128 v[180:183], v224 offset:34816
	ds_read_b128 v[184:187], v224 offset:35840
	ds_read_b128 v[188:191], v224 offset:36864
	ds_read_b128 v[192:195], v224 offset:37888
	ds_read_b128 v[196:199], v224 offset:38912
	ds_read_b128 v[200:203], v224 offset:39936
	s_setprio 0
	global_load_lds_dwordx4 v140, s[0:1]
	s_mov_b32 m0, s56
	s_nop 0
	global_load_lds_dwordx4 v142, s[0:1]
	s_waitcnt vmcnt(10) lgkmcnt(8)
	s_setprio 1
	s_barrier
	s_waitcnt lgkmcnt(0)
	v_mfma_f32_16x16x32_bf16 v[128:131], v[132:135], v[172:175], v[128:131]
	v_mfma_f32_16x16x32_bf16 v[124:127], v[156:159], v[172:175], v[124:127]
	v_mfma_f32_16x16x32_bf16 v[120:123], v[132:135], v[180:183], v[120:123]
	v_mfma_f32_16x16x32_bf16 v[116:119], v[156:159], v[180:183], v[116:119]
	v_mfma_f32_16x16x32_bf16 v[112:115], v[132:135], v[188:191], v[112:115]
	v_mfma_f32_16x16x32_bf16 v[108:111], v[156:159], v[188:191], v[108:111]
	v_mfma_f32_16x16x32_bf16 v[104:107], v[132:135], v[196:199], v[104:107]
	v_mfma_f32_16x16x32_bf16 v[100:103], v[156:159], v[196:199], v[100:103]
	v_mfma_f32_16x16x32_bf16 v[128:131], v[136:139], v[176:179], v[128:131]
	v_mfma_f32_16x16x32_bf16 v[124:127], v[160:163], v[176:179], v[124:127]
	v_mfma_f32_16x16x32_bf16 v[120:123], v[136:139], v[184:187], v[120:123]
	v_mfma_f32_16x16x32_bf16 v[116:119], v[160:163], v[184:187], v[116:119]
	v_mfma_f32_16x16x32_bf16 v[112:115], v[136:139], v[192:195], v[112:115]
	v_mfma_f32_16x16x32_bf16 v[108:111], v[160:163], v[192:195], v[108:111]
	v_mfma_f32_16x16x32_bf16 v[104:107], v[136:139], v[200:203], v[104:107]
	v_mfma_f32_16x16x32_bf16 v[100:103], v[160:163], v[200:203], v[100:103]
	s_barrier
	s_add_i32 s27, 0, 0x1c000
	s_add_i32 s0, s26, s17
	v_add_u32_e32 v216, s27, v222
	v_lshl_add_u64 v[164:165], v[164:165], 0, s[12:13]
	s_mov_b32 m0, s0
	ds_read_b128 v[204:207], v216
	ds_read_b128 v[208:211], v216 offset:1024
	ds_read_b128 v[212:215], v216 offset:2048
	ds_read_b128 v[216:219], v216 offset:3072
	s_setprio 0
	global_load_lds_dwordx4 v[164:165], off
	v_lshl_add_u64 v[164:165], v[166:167], 0, s[12:13]
	s_add_i32 m0, s0, 0x2000
	s_nop 0
	global_load_lds_dwordx4 v[164:165], off
	s_waitcnt vmcnt(10)
	s_setprio 1
	s_barrier
	s_waitcnt lgkmcnt(0)
	v_mfma_f32_16x16x32_bf16 v[64:67], v[204:207], v[172:175], v[64:67]
	v_mfma_f32_16x16x32_bf16 v[60:63], v[212:215], v[172:175], v[60:63]
	v_mfma_f32_16x16x32_bf16 v[56:59], v[204:207], v[180:183], v[56:59]
	v_mfma_f32_16x16x32_bf16 v[52:55], v[212:215], v[180:183], v[52:55]
	v_mfma_f32_16x16x32_bf16 v[48:51], v[204:207], v[188:191], v[48:51]
	v_mfma_f32_16x16x32_bf16 v[44:47], v[212:215], v[188:191], v[44:47]
	v_mfma_f32_16x16x32_bf16 v[40:43], v[204:207], v[196:199], v[40:43]
	v_mfma_f32_16x16x32_bf16 v[36:39], v[212:215], v[196:199], v[36:39]
	v_mfma_f32_16x16x32_bf16 v[64:67], v[208:211], v[176:179], v[64:67]
	v_mfma_f32_16x16x32_bf16 v[60:63], v[216:219], v[176:179], v[60:63]
	v_mfma_f32_16x16x32_bf16 v[56:59], v[208:211], v[184:187], v[56:59]
	v_mfma_f32_16x16x32_bf16 v[52:55], v[216:219], v[184:187], v[52:55]
	v_mfma_f32_16x16x32_bf16 v[48:51], v[208:211], v[192:195], v[48:51]
	v_mfma_f32_16x16x32_bf16 v[44:47], v[216:219], v[192:195], v[44:47]
	v_mfma_f32_16x16x32_bf16 v[40:43], v[208:211], v[200:203], v[40:43]
	v_mfma_f32_16x16x32_bf16 v[36:39], v[216:219], v[200:203], v[36:39]
	s_barrier
	s_mov_b32 m0, s59
	v_lshl_add_u64 v[164:165], v[168:169], 0, s[12:13]
	ds_read_b128 v[172:175], v224 offset:49152
	ds_read_b128 v[176:179], v224 offset:50176
	ds_read_b128 v[180:183], v224 offset:51200
	ds_read_b128 v[184:187], v224 offset:52224
	ds_read_b128 v[188:191], v224 offset:53248
	ds_read_b128 v[192:195], v224 offset:54272
	ds_read_b128 v[196:199], v224 offset:55296
	ds_read_b128 v[200:203], v224 offset:56320
	s_setprio 0
	global_load_lds_dwordx4 v[164:165], off
	v_lshl_add_u64 v[164:165], v[220:221], 0, s[12:13]
	s_mov_b32 m0, s68
	s_nop 0
	global_load_lds_dwordx4 v[164:165], off
	s_waitcnt vmcnt(10)
	s_setprio 1
	s_barrier
	s_waitcnt lgkmcnt(0)
	v_mfma_f32_16x16x32_bf16 v[96:99], v[132:135], v[172:175], v[96:99]
	v_mfma_f32_16x16x32_bf16 v[92:95], v[156:159], v[172:175], v[92:95]
	v_mfma_f32_16x16x32_bf16 v[88:91], v[132:135], v[180:183], v[88:91]
	v_mfma_f32_16x16x32_bf16 v[84:87], v[156:159], v[180:183], v[84:87]
	v_mfma_f32_16x16x32_bf16 v[80:83], v[132:135], v[188:191], v[80:83]
	v_mfma_f32_16x16x32_bf16 v[76:79], v[156:159], v[188:191], v[76:79]
	v_mfma_f32_16x16x32_bf16 v[72:75], v[132:135], v[196:199], v[72:75]
	v_mfma_f32_16x16x32_bf16 v[68:71], v[156:159], v[196:199], v[68:71]
	v_mfma_f32_16x16x32_bf16 v[96:99], v[136:139], v[176:179], v[96:99]
	v_mfma_f32_16x16x32_bf16 v[92:95], v[160:163], v[176:179], v[92:95]
	v_mfma_f32_16x16x32_bf16 v[88:91], v[136:139], v[184:187], v[88:91]
	v_mfma_f32_16x16x32_bf16 v[84:87], v[160:163], v[184:187], v[84:87]
	v_mfma_f32_16x16x32_bf16 v[80:83], v[136:139], v[192:195], v[80:83]
	v_mfma_f32_16x16x32_bf16 v[76:79], v[160:163], v[192:195], v[76:79]
	v_mfma_f32_16x16x32_bf16 v[72:75], v[136:139], v[200:203], v[72:75]
	v_mfma_f32_16x16x32_bf16 v[68:71], v[160:163], v[200:203], v[68:71]
	s_barrier
	s_add_u32 s0, s30, 0xb0080
	s_addc_u32 s1, s31, 0
	s_add_i32 s26, s27, s17
	s_setprio 0
	s_mov_b32 m0, s26
	s_nop 0
	global_load_lds_dwordx4 v26, s[0:1]
	s_add_i32 m0, s26, 0x2000
	s_nop 0
	global_load_lds_dwordx4 v144, s[0:1]
	v_add_u32_e32 v160, 0x10000, v222
	ds_read_b128 v[132:135], v160
	ds_read_b128 v[136:139], v160 offset:1024
	ds_read_b128 v[156:159], v160 offset:2048
	ds_read_b128 v[160:163], v160 offset:3072
	s_add_i32 s81, s81, 2
	s_add_u32 s44, s44, 0x100
	s_addc_u32 s45, s45, 0
	s_mov_b64 s[26:27], s[28:29]
	s_cmp_gt_u32 s81, 41
	s_cbranch_scc1 .Lth__1156
	s_add_u32 s28, s26, 0x100
	s_addc_u32 s29, s27, 0
	s_add_i32 s0, 0, 0x10000
	s_cmp_eq_u32 s81, 40
	s_cselect_b32 s35, s43, s29
	s_cselect_b32 s34, s42, s28
	s_cselect_b32 s31, s23, s45
	s_cselect_b32 s30, s22, s44
	s_cmp_gt_u32 s81, 41
